# GEMM tile loops: with no next tile, the unused next-tile staging of the last K-pair re-reads the current tile's last two K-tiles (L2-resident) instead of its first two
# speedup vs baseline: 1.0006x; 1.0006x over previous
.LBB0_151:
	s_ashr_i32 s37, s36, 31
	s_lshl_b64 s[38:39], s[36:37], 19
	s_add_u32 s38, s74, s38
	s_addc_u32 s39, s75, s39
	s_add_u32 s98, s70, 0x700
	s_addc_u32 s99, s71, 0
	s_and_b64 s[40:41], s[6:7], exec
	s_cselect_b32 s11, s39, s99
	s_cselect_b32 s22, s38, s98
	s_ashr_i32 s35, s34, 31
	s_lshl_b64 s[40:41], s[34:35], 19
	s_add_u32 s40, s20, s40
	s_addc_u32 s41, s21, s41
	s_add_u32 s98, s78, 0x700
	s_addc_u32 s99, s79, 0
	s_and_b64 s[80:81], s[6:7], exec
	s_cselect_b32 s35, s41, s99
	s_cselect_b32 s37, s40, s98
	s_add_u32 s70, s70, 0x40080
	s_addc_u32 s71, s71, 0
	s_add_u32 s94, s78, 0x100
	s_addc_u32 s95, s79, 0
	s_mov_b32 s96, -2
	s_waitcnt lgkmcnt(0)
	ds_read_b128 v[128:131], v192
	ds_read_b128 v[132:135], v192 offset:1024
	ds_read_b128 v[136:139], v192 offset:2048
	ds_read_b128 v[140:143], v192 offset:3072
	ds_read_b128 v[164:167], v193
	ds_read_b128 v[168:171], v193 offset:1024
	ds_read_b128 v[172:175], v193 offset:2048
	ds_read_b128 v[176:179], v193 offset:3072
	s_add_u32 s78, s70, 0xfffc0080
	s_addc_u32 s79, s71, -1
	s_cmp_eq_u32 s96, 12
	s_cselect_b32 s81, s11, s79
	s_cselect_b32 s80, s22, s78
	s_cselect_b32 s79, s35, s95
	s_cselect_b32 s78, s37, s94
	v_lshl_add_u64 v[228:229], s[70:71], 0, v[156:157]
	s_add_i32 m0, s82, 0xc000
	ds_read_b128 v[196:199], v194
	ds_read_b128 v[200:203], v194 offset:1024
	ds_read_b128 v[204:207], v194 offset:2048
	ds_read_b128 v[208:211], v194 offset:3072
	ds_read_b128 v[212:215], v194 offset:4096
	ds_read_b128 v[216:219], v194 offset:5120
	ds_read_b128 v[220:223], v194 offset:6144
	ds_read_b128 v[224:227], v194 offset:7168
	global_load_lds_dwordx4 v[228:229], off
	v_lshl_add_u64 v[228:229], s[70:71], 0, v[158:159]
	s_add_i32 m0, s82, 0xe000
	s_nop 0
	global_load_lds_dwordx4 v[228:229], off
	s_waitcnt vmcnt(8)
	s_waitcnt lgkmcnt(0)
	s_barrier
	s_waitcnt lgkmcnt(0)
	v_mfma_f32_16x16x32_bf16 v[124:127], v[128:131], v[196:199], 0
	v_mfma_f32_16x16x32_bf16 v[120:123], v[136:139], v[196:199], 0
	v_mfma_f32_16x16x32_bf16 v[108:111], v[128:131], v[204:207], 0
	v_mfma_f32_16x16x32_bf16 v[104:107], v[136:139], v[204:207], 0
	v_mfma_f32_16x16x32_bf16 v[92:95], v[128:131], v[212:215], 0
	v_mfma_f32_16x16x32_bf16 v[88:91], v[136:139], v[212:215], 0
	v_mfma_f32_16x16x32_bf16 v[76:79], v[128:131], v[220:223], 0
	v_mfma_f32_16x16x32_bf16 v[72:75], v[136:139], v[220:223], 0
	v_mfma_f32_16x16x32_bf16 v[124:127], v[132:135], v[200:203], v[124:127]
	v_mfma_f32_16x16x32_bf16 v[120:123], v[140:143], v[200:203], v[120:123]
	v_mfma_f32_16x16x32_bf16 v[108:111], v[132:135], v[208:211], v[108:111]
	v_mfma_f32_16x16x32_bf16 v[104:107], v[140:143], v[208:211], v[104:107]
	v_mfma_f32_16x16x32_bf16 v[92:95], v[132:135], v[216:219], v[92:95]
	v_mfma_f32_16x16x32_bf16 v[88:91], v[140:143], v[216:219], v[88:91]
	v_mfma_f32_16x16x32_bf16 v[76:79], v[132:135], v[224:227], v[76:79]
	v_mfma_f32_16x16x32_bf16 v[72:75], v[140:143], v[224:227], v[72:75]
	v_mfma_f32_16x16x32_bf16 v[116:119], v[164:167], v[196:199], 0
	v_mfma_f32_16x16x32_bf16 v[112:115], v[172:175], v[196:199], 0
	v_mfma_f32_16x16x32_bf16 v[100:103], v[164:167], v[204:207], 0
	v_mfma_f32_16x16x32_bf16 v[96:99], v[172:175], v[204:207], 0
	v_mfma_f32_16x16x32_bf16 v[84:87], v[164:167], v[212:215], 0
	v_mfma_f32_16x16x32_bf16 v[80:83], v[172:175], v[212:215], 0
	v_mfma_f32_16x16x32_bf16 v[68:71], v[164:167], v[220:223], 0
	v_mfma_f32_16x16x32_bf16 v[64:67], v[172:175], v[220:223], 0
	v_mfma_f32_16x16x32_bf16 v[116:119], v[168:171], v[200:203], v[116:119]
	v_mfma_f32_16x16x32_bf16 v[112:115], v[176:179], v[200:203], v[112:115]
	v_mfma_f32_16x16x32_bf16 v[100:103], v[168:171], v[208:211], v[100:103]
	v_mfma_f32_16x16x32_bf16 v[96:99], v[176:179], v[208:211], v[96:99]
	v_mfma_f32_16x16x32_bf16 v[84:87], v[168:171], v[216:219], v[84:87]
	v_mfma_f32_16x16x32_bf16 v[80:83], v[176:179], v[216:219], v[80:83]
	s_setprio 3
	s_barrier
	v_mfma_f32_16x16x32_bf16 v[68:71], v[168:171], v[224:227], v[68:71]
	v_mfma_f32_16x16x32_bf16 v[64:67], v[176:179], v[224:227], v[64:67]
	s_setprio 0
	s_add_i32 s97, s90, s33
	v_lshl_add_u64 v[228:229], s[78:79], 0, v[146:147]
	s_mov_b32 m0, s97
	ds_read_b128 v[196:199], v194 offset:16384
	ds_read_b128 v[200:203], v194 offset:17408
	ds_read_b128 v[204:207], v194 offset:18432
	ds_read_b128 v[208:211], v194 offset:19456
	ds_read_b128 v[212:215], v194 offset:20480
	ds_read_b128 v[216:219], v194 offset:21504
	ds_read_b128 v[220:223], v194 offset:22528
	ds_read_b128 v[224:227], v194 offset:23552
	global_load_lds_dwordx4 v[228:229], off
	s_add_i32 m0, s97, 0x2000
	s_add_u32 vcc_lo, s78, 0x40000
	v_lshl_add_u64 v[230:231], s[78:79], 0, v[150:151]
	s_addc_u32 vcc_hi, s79, 0
	s_add_i32 s97, s91, s33
	global_load_lds_dwordx4 v[230:231], off
	v_lshl_add_u64 v[232:233], vcc, 0, v[146:147]
	s_mov_b32 m0, s97
	global_load_lds_dwordx4 v[232:233], off
	v_lshl_add_u64 v[232:233], vcc, 0, v[150:151]
	s_add_i32 m0, s97, 0x2000
	s_nop 0
	global_load_lds_dwordx4 v[232:233], off
	s_waitcnt vmcnt(6)
	s_waitcnt lgkmcnt(0)
	s_barrier
	s_waitcnt lgkmcnt(0)
	v_mfma_f32_16x16x32_bf16 v[60:63], v[128:131], v[196:199], 0
	v_mfma_f32_16x16x32_bf16 v[56:59], v[136:139], v[196:199], 0
	v_mfma_f32_16x16x32_bf16 v[44:47], v[128:131], v[204:207], 0
	v_mfma_f32_16x16x32_bf16 v[40:43], v[136:139], v[204:207], 0
	v_mfma_f32_16x16x32_bf16 v[28:31], v[128:131], v[212:215], 0
	v_mfma_f32_16x16x32_bf16 v[24:27], v[136:139], v[212:215], 0
	v_mfma_f32_16x16x32_bf16 v[12:15], v[128:131], v[220:223], 0
	v_mfma_f32_16x16x32_bf16 v[8:11], v[136:139], v[220:223], 0
	v_mfma_f32_16x16x32_bf16 v[60:63], v[132:135], v[200:203], v[60:63]
	v_mfma_f32_16x16x32_bf16 v[56:59], v[140:143], v[200:203], v[56:59]
	v_mfma_f32_16x16x32_bf16 v[44:47], v[132:135], v[208:211], v[44:47]
	v_mfma_f32_16x16x32_bf16 v[40:43], v[140:143], v[208:211], v[40:43]
	v_mfma_f32_16x16x32_bf16 v[28:31], v[132:135], v[216:219], v[28:31]
	v_mfma_f32_16x16x32_bf16 v[24:27], v[140:143], v[216:219], v[24:27]
	v_mfma_f32_16x16x32_bf16 v[12:15], v[132:135], v[224:227], v[12:15]
	v_mfma_f32_16x16x32_bf16 v[8:11], v[140:143], v[224:227], v[8:11]
	v_mfma_f32_16x16x32_bf16 v[52:55], v[164:167], v[196:199], 0
	v_mfma_f32_16x16x32_bf16 v[48:51], v[172:175], v[196:199], 0
	v_mfma_f32_16x16x32_bf16 v[36:39], v[164:167], v[204:207], 0
	v_mfma_f32_16x16x32_bf16 v[32:35], v[172:175], v[204:207], 0
	v_mfma_f32_16x16x32_bf16 v[20:23], v[164:167], v[212:215], 0
	v_mfma_f32_16x16x32_bf16 v[16:19], v[172:175], v[212:215], 0
	v_mfma_f32_16x16x32_bf16 v[4:7], v[164:167], v[220:223], 0
	v_mfma_f32_16x16x32_bf16 v[0:3], v[172:175], v[220:223], 0
	v_mfma_f32_16x16x32_bf16 v[52:55], v[168:171], v[200:203], v[52:55]
	v_mfma_f32_16x16x32_bf16 v[48:51], v[176:179], v[200:203], v[48:51]
	v_mfma_f32_16x16x32_bf16 v[36:39], v[168:171], v[208:211], v[36:39]
	v_mfma_f32_16x16x32_bf16 v[32:35], v[176:179], v[208:211], v[32:35]
	v_mfma_f32_16x16x32_bf16 v[20:23], v[168:171], v[216:219], v[20:23]
	v_mfma_f32_16x16x32_bf16 v[16:19], v[176:179], v[216:219], v[16:19]
	s_setprio 3
	s_barrier
	v_mfma_f32_16x16x32_bf16 v[4:7], v[168:171], v[224:227], v[4:7]
	v_mfma_f32_16x16x32_bf16 v[0:3], v[176:179], v[224:227], v[0:3]
	s_setprio 0
	s_add_i32 s97, 0, 0x18000
	s_add_i32 vcc_lo, 0, 0x1c000
	v_add_u32_e32 v140, s97, v180
	v_add_u32_e32 v152, vcc_lo, v180
	ds_read_b128 v[128:131], v140
	ds_read_b128 v[132:135], v140 offset:1024
	ds_read_b128 v[136:139], v140 offset:2048
	ds_read_b128 v[140:143], v140 offset:3072
	ds_read_b128 v[164:167], v152
	ds_read_b128 v[168:171], v152 offset:1024
	ds_read_b128 v[172:175], v152 offset:2048
	ds_read_b128 v[176:179], v152 offset:3072
	v_lshl_add_u64 v[232:233], s[80:81], 0, v[144:145]
	s_mov_b32 m0, s82
	v_lshl_add_u64 v[234:235], s[80:81], 0, v[148:149]
	global_load_lds_dwordx4 v[232:233], off
	s_mov_b32 m0, s83
	s_nop 0
	global_load_lds_dwordx4 v[234:235], off
	s_add_u32 s80, s80, 0x40000
	s_addc_u32 s81, s81, 0
	s_mov_b32 m0, s84
	v_lshl_add_u64 v[236:237], s[80:81], 0, v[144:145]
	ds_read_b128 v[196:199], v194 offset:32768
	ds_read_b128 v[200:203], v194 offset:33792
	ds_read_b128 v[204:207], v194 offset:34816
	ds_read_b128 v[208:211], v194 offset:35840
	ds_read_b128 v[212:215], v194 offset:36864
	ds_read_b128 v[216:219], v194 offset:37888
	ds_read_b128 v[220:223], v194 offset:38912
	ds_read_b128 v[224:227], v194 offset:39936
	global_load_lds_dwordx4 v[236:237], off
	v_lshl_add_u64 v[236:237], s[80:81], 0, v[148:149]
	s_mov_b32 m0, s85
	s_nop 0
	global_load_lds_dwordx4 v[236:237], off
	s_waitcnt vmcnt(8)
	s_waitcnt lgkmcnt(0)
	s_barrier
	s_waitcnt lgkmcnt(0)
	v_mfma_f32_16x16x32_bf16 v[124:127], v[128:131], v[196:199], v[124:127]
	v_mfma_f32_16x16x32_bf16 v[120:123], v[136:139], v[196:199], v[120:123]
	v_mfma_f32_16x16x32_bf16 v[108:111], v[128:131], v[204:207], v[108:111]
	v_mfma_f32_16x16x32_bf16 v[104:107], v[136:139], v[204:207], v[104:107]
	v_mfma_f32_16x16x32_bf16 v[92:95], v[128:131], v[212:215], v[92:95]
	v_mfma_f32_16x16x32_bf16 v[88:91], v[136:139], v[212:215], v[88:91]
	v_mfma_f32_16x16x32_bf16 v[76:79], v[128:131], v[220:223], v[76:79]
	v_mfma_f32_16x16x32_bf16 v[72:75], v[136:139], v[220:223], v[72:75]
	v_mfma_f32_16x16x32_bf16 v[124:127], v[132:135], v[200:203], v[124:127]
	v_mfma_f32_16x16x32_bf16 v[120:123], v[140:143], v[200:203], v[120:123]
	v_mfma_f32_16x16x32_bf16 v[108:111], v[132:135], v[208:211], v[108:111]
	v_mfma_f32_16x16x32_bf16 v[104:107], v[140:143], v[208:211], v[104:107]
	v_mfma_f32_16x16x32_bf16 v[92:95], v[132:135], v[216:219], v[92:95]
	v_mfma_f32_16x16x32_bf16 v[88:91], v[140:143], v[216:219], v[88:91]
	v_mfma_f32_16x16x32_bf16 v[76:79], v[132:135], v[224:227], v[76:79]
	v_mfma_f32_16x16x32_bf16 v[72:75], v[140:143], v[224:227], v[72:75]
	v_mfma_f32_16x16x32_bf16 v[116:119], v[164:167], v[196:199], v[116:119]
	v_mfma_f32_16x16x32_bf16 v[112:115], v[172:175], v[196:199], v[112:115]
	v_mfma_f32_16x16x32_bf16 v[100:103], v[164:167], v[204:207], v[100:103]
	v_mfma_f32_16x16x32_bf16 v[96:99], v[172:175], v[204:207], v[96:99]
	v_mfma_f32_16x16x32_bf16 v[84:87], v[164:167], v[212:215], v[84:87]
	v_mfma_f32_16x16x32_bf16 v[80:83], v[172:175], v[212:215], v[80:83]
	v_mfma_f32_16x16x32_bf16 v[68:71], v[164:167], v[220:223], v[68:71]
	v_mfma_f32_16x16x32_bf16 v[64:67], v[172:175], v[220:223], v[64:67]
	v_mfma_f32_16x16x32_bf16 v[116:119], v[168:171], v[200:203], v[116:119]
	v_mfma_f32_16x16x32_bf16 v[112:115], v[176:179], v[200:203], v[112:115]
	v_mfma_f32_16x16x32_bf16 v[100:103], v[168:171], v[208:211], v[100:103]
	v_mfma_f32_16x16x32_bf16 v[96:99], v[176:179], v[208:211], v[96:99]
	v_mfma_f32_16x16x32_bf16 v[84:87], v[168:171], v[216:219], v[84:87]
	v_mfma_f32_16x16x32_bf16 v[80:83], v[176:179], v[216:219], v[80:83]
	s_setprio 3
	s_barrier
	v_mfma_f32_16x16x32_bf16 v[68:71], v[168:171], v[224:227], v[68:71]
	v_mfma_f32_16x16x32_bf16 v[64:67], v[176:179], v[224:227], v[64:67]
	s_setprio 0
	s_add_i32 s80, s97, s33
	v_lshl_add_u64 v[228:229], v[228:229], 0, s[26:27]
	s_mov_b32 m0, s80
	ds_read_b128 v[196:199], v194 offset:49152
	ds_read_b128 v[200:203], v194 offset:50176
	ds_read_b128 v[204:207], v194 offset:51200
	ds_read_b128 v[208:211], v194 offset:52224
	ds_read_b128 v[212:215], v194 offset:53248
	ds_read_b128 v[216:219], v194 offset:54272
	ds_read_b128 v[220:223], v194 offset:55296
	ds_read_b128 v[224:227], v194 offset:56320
	global_load_lds_dwordx4 v[228:229], off
	s_add_i32 m0, s80, 0x2000
	s_add_u32 s78, s78, 0x40080
	v_lshl_add_u64 v[228:229], v[230:231], 0, s[26:27]
	s_addc_u32 s79, s79, 0
	s_add_i32 s80, vcc_lo, s33
	global_load_lds_dwordx4 v[228:229], off
	v_lshl_add_u64 v[228:229], s[78:79], 0, v[146:147]
	s_mov_b32 m0, s80
	s_nop 0
	global_load_lds_dwordx4 v[228:229], off
	v_lshl_add_u64 v[228:229], s[78:79], 0, v[150:151]
	s_add_i32 m0, s80, 0x2000
	s_nop 0
	global_load_lds_dwordx4 v[228:229], off
	s_waitcnt vmcnt(6)
	s_waitcnt lgkmcnt(0)
	s_barrier
	s_waitcnt lgkmcnt(0)
	v_mfma_f32_16x16x32_bf16 v[60:63], v[128:131], v[196:199], v[60:63]
	v_mfma_f32_16x16x32_bf16 v[56:59], v[136:139], v[196:199], v[56:59]
	v_mfma_f32_16x16x32_bf16 v[44:47], v[128:131], v[204:207], v[44:47]
	v_mfma_f32_16x16x32_bf16 v[40:43], v[136:139], v[204:207], v[40:43]
	v_mfma_f32_16x16x32_bf16 v[28:31], v[128:131], v[212:215], v[28:31]
	v_mfma_f32_16x16x32_bf16 v[24:27], v[136:139], v[212:215], v[24:27]
	v_mfma_f32_16x16x32_bf16 v[12:15], v[128:131], v[220:223], v[12:15]
	v_mfma_f32_16x16x32_bf16 v[8:11], v[136:139], v[220:223], v[8:11]
	v_mfma_f32_16x16x32_bf16 v[60:63], v[132:135], v[200:203], v[60:63]
	v_mfma_f32_16x16x32_bf16 v[56:59], v[140:143], v[200:203], v[56:59]
	v_mfma_f32_16x16x32_bf16 v[44:47], v[132:135], v[208:211], v[44:47]
	v_mfma_f32_16x16x32_bf16 v[40:43], v[140:143], v[208:211], v[40:43]
	v_mfma_f32_16x16x32_bf16 v[28:31], v[132:135], v[216:219], v[28:31]
	v_mfma_f32_16x16x32_bf16 v[24:27], v[140:143], v[216:219], v[24:27]
	v_mfma_f32_16x16x32_bf16 v[12:15], v[132:135], v[224:227], v[12:15]
	v_mfma_f32_16x16x32_bf16 v[8:11], v[140:143], v[224:227], v[8:11]
	v_mfma_f32_16x16x32_bf16 v[52:55], v[164:167], v[196:199], v[52:55]
	v_mfma_f32_16x16x32_bf16 v[48:51], v[172:175], v[196:199], v[48:51]
	v_mfma_f32_16x16x32_bf16 v[36:39], v[164:167], v[204:207], v[36:39]
	v_mfma_f32_16x16x32_bf16 v[32:35], v[172:175], v[204:207], v[32:35]
	v_mfma_f32_16x16x32_bf16 v[20:23], v[164:167], v[212:215], v[20:23]
	v_mfma_f32_16x16x32_bf16 v[16:19], v[172:175], v[212:215], v[16:19]
	v_mfma_f32_16x16x32_bf16 v[4:7], v[164:167], v[220:223], v[4:7]
	v_mfma_f32_16x16x32_bf16 v[0:3], v[172:175], v[220:223], v[0:3]
	v_mfma_f32_16x16x32_bf16 v[52:55], v[168:171], v[200:203], v[52:55]
	v_mfma_f32_16x16x32_bf16 v[48:51], v[176:179], v[200:203], v[48:51]
	v_mfma_f32_16x16x32_bf16 v[36:39], v[168:171], v[208:211], v[36:39]
	v_mfma_f32_16x16x32_bf16 v[32:35], v[176:179], v[208:211], v[32:35]
	v_mfma_f32_16x16x32_bf16 v[20:23], v[168:171], v[216:219], v[20:23]
	v_mfma_f32_16x16x32_bf16 v[16:19], v[176:179], v[216:219], v[16:19]
	s_setprio 3
	s_barrier
	v_mfma_f32_16x16x32_bf16 v[4:7], v[168:171], v[224:227], v[4:7]
	v_mfma_f32_16x16x32_bf16 v[0:3], v[176:179], v[224:227], v[0:3]
	s_setprio 0
	v_lshl_add_u64 v[228:229], v[232:233], 0, s[26:27]
	s_mov_b32 m0, s87
	s_nop 0
	global_load_lds_dwordx4 v[228:229], off
	v_lshl_add_u64 v[228:229], v[234:235], 0, s[26:27]
	s_mov_b32 m0, s88
	s_nop 0
	global_load_lds_dwordx4 v[228:229], off
	s_add_i32 s96, s96, 2
	s_add_u32 s70, s70, 0x100
	s_addc_u32 s71, s71, 0
	s_add_u32 s94, s94, 0x100
	s_addc_u32 s95, s95, 0
	s_cmp_gt_u32 s96, 13

.LBB0_616:
	s_ashr_i32 s17, s16, 31
	s_lshl_b64 s[18:19], s[16:17], 19
	s_add_u32 s18, s48, s18
	s_addc_u32 s19, s49, s19
	s_add_u32 s98, s24, 0x700
	s_addc_u32 s99, s25, 0
	s_and_b64 s[20:21], s[4:5], exec
	s_cselect_b32 s17, s19, s99
	s_cselect_b32 s23, s18, s98
	s_ashr_i32 s15, s14, 31
	s_lshl_b64 s[20:21], s[14:15], 19
	s_add_u32 s20, s30, s20
	s_addc_u32 s21, s31, s21
	s_add_u32 s98, s26, 0x700
	s_addc_u32 s99, s27, 0
	s_and_b64 s[28:29], s[4:5], exec
	s_cselect_b32 s15, s21, s99
	s_cselect_b32 s46, s20, s98
	s_add_u32 s24, s24, 0x40080
	s_addc_u32 s25, s25, 0
	s_add_u32 s47, s26, 0x100
	s_addc_u32 s50, s27, 0
	s_mov_b32 s51, -2
	s_waitcnt lgkmcnt(0)
	ds_read_b128 v[144:147], v151
	ds_read_b128 v[156:159], v151 offset:1024
	ds_read_b128 v[160:163], v151 offset:2048
	ds_read_b128 v[164:167], v151 offset:3072
	ds_read_b128 v[168:171], v152
	ds_read_b128 v[172:175], v152 offset:1024
	ds_read_b128 v[176:179], v152 offset:2048
	ds_read_b128 v[184:187], v152 offset:3072
	s_add_u32 s26, s24, 0xfffc0080
	s_addc_u32 s27, s25, -1
	s_cmp_eq_u32 s51, 12
	s_cselect_b32 s29, s17, s27
	s_cselect_b32 s28, s23, s26
	s_cselect_b32 s27, s15, s50
	s_cselect_b32 s26, s46, s47
	v_lshl_add_u64 v[220:221], s[24:25], 0, v[136:137]
	s_add_i32 m0, s34, 0xc000
	ds_read_b128 v[188:191], v153
	ds_read_b128 v[192:195], v153 offset:1024
	ds_read_b128 v[196:199], v153 offset:2048
	ds_read_b128 v[200:203], v153 offset:3072
	ds_read_b128 v[204:207], v153 offset:4096
	ds_read_b128 v[208:211], v153 offset:5120
	ds_read_b128 v[212:215], v153 offset:6144
	ds_read_b128 v[216:219], v153 offset:7168
	global_load_lds_dwordx4 v[220:221], off
	v_lshl_add_u64 v[220:221], s[24:25], 0, v[138:139]
	s_add_i32 m0, s34, 0xe000
	s_nop 0
	global_load_lds_dwordx4 v[220:221], off
	s_waitcnt vmcnt(8)
	s_waitcnt lgkmcnt(0)
	s_barrier
	s_waitcnt lgkmcnt(0)
	v_mfma_f32_16x16x32_bf16 v[124:127], v[144:147], v[188:191], 0
	v_mfma_f32_16x16x32_bf16 v[120:123], v[160:163], v[188:191], 0
	v_mfma_f32_16x16x32_bf16 v[108:111], v[144:147], v[196:199], 0
	v_mfma_f32_16x16x32_bf16 v[104:107], v[160:163], v[196:199], 0
	v_mfma_f32_16x16x32_bf16 v[92:95], v[144:147], v[204:207], 0
	v_mfma_f32_16x16x32_bf16 v[88:91], v[160:163], v[204:207], 0
	v_mfma_f32_16x16x32_bf16 v[76:79], v[144:147], v[212:215], 0
	v_mfma_f32_16x16x32_bf16 v[72:75], v[160:163], v[212:215], 0
	v_mfma_f32_16x16x32_bf16 v[124:127], v[156:159], v[192:195], v[124:127]
	v_mfma_f32_16x16x32_bf16 v[120:123], v[164:167], v[192:195], v[120:123]
	v_mfma_f32_16x16x32_bf16 v[108:111], v[156:159], v[200:203], v[108:111]
	v_mfma_f32_16x16x32_bf16 v[104:107], v[164:167], v[200:203], v[104:107]
	v_mfma_f32_16x16x32_bf16 v[92:95], v[156:159], v[208:211], v[92:95]
	v_mfma_f32_16x16x32_bf16 v[88:91], v[164:167], v[208:211], v[88:91]
	v_mfma_f32_16x16x32_bf16 v[76:79], v[156:159], v[216:219], v[76:79]
	v_mfma_f32_16x16x32_bf16 v[72:75], v[164:167], v[216:219], v[72:75]
	v_mfma_f32_16x16x32_bf16 v[116:119], v[168:171], v[188:191], 0
	v_mfma_f32_16x16x32_bf16 v[112:115], v[176:179], v[188:191], 0
	v_mfma_f32_16x16x32_bf16 v[100:103], v[168:171], v[196:199], 0
	v_mfma_f32_16x16x32_bf16 v[96:99], v[176:179], v[196:199], 0
	v_mfma_f32_16x16x32_bf16 v[84:87], v[168:171], v[204:207], 0
	v_mfma_f32_16x16x32_bf16 v[80:83], v[176:179], v[204:207], 0
	v_mfma_f32_16x16x32_bf16 v[68:71], v[168:171], v[212:215], 0
	v_mfma_f32_16x16x32_bf16 v[64:67], v[176:179], v[212:215], 0
	v_mfma_f32_16x16x32_bf16 v[116:119], v[172:175], v[192:195], v[116:119]
	v_mfma_f32_16x16x32_bf16 v[112:115], v[184:187], v[192:195], v[112:115]
	v_mfma_f32_16x16x32_bf16 v[100:103], v[172:175], v[200:203], v[100:103]
	v_mfma_f32_16x16x32_bf16 v[96:99], v[184:187], v[200:203], v[96:99]
	v_mfma_f32_16x16x32_bf16 v[84:87], v[172:175], v[208:211], v[84:87]
	v_mfma_f32_16x16x32_bf16 v[80:83], v[184:187], v[208:211], v[80:83]
	s_setprio 3
	s_barrier
	v_mfma_f32_16x16x32_bf16 v[68:71], v[172:175], v[216:219], v[68:71]
	v_mfma_f32_16x16x32_bf16 v[64:67], v[184:187], v[216:219], v[64:67]
	s_setprio 0
	s_add_i32 s52, s41, s33
	v_lshl_add_u64 v[220:221], s[26:27], 0, v[130:131]
	s_mov_b32 m0, s52
	ds_read_b128 v[188:191], v153 offset:16384
	ds_read_b128 v[192:195], v153 offset:17408
	ds_read_b128 v[196:199], v153 offset:18432
	ds_read_b128 v[200:203], v153 offset:19456
	ds_read_b128 v[204:207], v153 offset:20480
	ds_read_b128 v[208:211], v153 offset:21504
	ds_read_b128 v[212:215], v153 offset:22528
	ds_read_b128 v[216:219], v153 offset:23552
	global_load_lds_dwordx4 v[220:221], off
	s_add_i32 m0, s52, 0x2000
	s_add_u32 s52, s26, 0x40000
	v_lshl_add_u64 v[222:223], s[26:27], 0, v[134:135]
	s_addc_u32 s53, s27, 0
	s_add_i32 s54, s42, s33
	global_load_lds_dwordx4 v[222:223], off
	v_lshl_add_u64 v[224:225], s[52:53], 0, v[130:131]
	s_mov_b32 m0, s54
	global_load_lds_dwordx4 v[224:225], off
	v_lshl_add_u64 v[224:225], s[52:53], 0, v[134:135]
	s_add_i32 m0, s54, 0x2000
	s_nop 0
	global_load_lds_dwordx4 v[224:225], off
	s_waitcnt vmcnt(6)
	s_waitcnt lgkmcnt(0)
	s_barrier
	s_waitcnt lgkmcnt(0)
	v_mfma_f32_16x16x32_bf16 v[60:63], v[144:147], v[188:191], 0
	v_mfma_f32_16x16x32_bf16 v[56:59], v[160:163], v[188:191], 0
	v_mfma_f32_16x16x32_bf16 v[44:47], v[144:147], v[196:199], 0
	v_mfma_f32_16x16x32_bf16 v[40:43], v[160:163], v[196:199], 0
	v_mfma_f32_16x16x32_bf16 v[28:31], v[144:147], v[204:207], 0
	v_mfma_f32_16x16x32_bf16 v[24:27], v[160:163], v[204:207], 0
	v_mfma_f32_16x16x32_bf16 v[12:15], v[144:147], v[212:215], 0
	v_mfma_f32_16x16x32_bf16 v[8:11], v[160:163], v[212:215], 0
	v_mfma_f32_16x16x32_bf16 v[60:63], v[156:159], v[192:195], v[60:63]
	v_mfma_f32_16x16x32_bf16 v[56:59], v[164:167], v[192:195], v[56:59]
	v_mfma_f32_16x16x32_bf16 v[44:47], v[156:159], v[200:203], v[44:47]
	v_mfma_f32_16x16x32_bf16 v[40:43], v[164:167], v[200:203], v[40:43]
	v_mfma_f32_16x16x32_bf16 v[28:31], v[156:159], v[208:211], v[28:31]
	v_mfma_f32_16x16x32_bf16 v[24:27], v[164:167], v[208:211], v[24:27]
	v_mfma_f32_16x16x32_bf16 v[12:15], v[156:159], v[216:219], v[12:15]
	v_mfma_f32_16x16x32_bf16 v[8:11], v[164:167], v[216:219], v[8:11]
	v_mfma_f32_16x16x32_bf16 v[52:55], v[168:171], v[188:191], 0
	v_mfma_f32_16x16x32_bf16 v[48:51], v[176:179], v[188:191], 0
	v_mfma_f32_16x16x32_bf16 v[36:39], v[168:171], v[196:199], 0
	v_mfma_f32_16x16x32_bf16 v[32:35], v[176:179], v[196:199], 0
	v_mfma_f32_16x16x32_bf16 v[20:23], v[168:171], v[204:207], 0
	v_mfma_f32_16x16x32_bf16 v[16:19], v[176:179], v[204:207], 0
	v_mfma_f32_16x16x32_bf16 v[4:7], v[168:171], v[212:215], 0
	v_mfma_f32_16x16x32_bf16 v[0:3], v[176:179], v[212:215], 0
	v_mfma_f32_16x16x32_bf16 v[52:55], v[172:175], v[192:195], v[52:55]
	v_mfma_f32_16x16x32_bf16 v[48:51], v[184:187], v[192:195], v[48:51]
	v_mfma_f32_16x16x32_bf16 v[36:39], v[172:175], v[200:203], v[36:39]
	v_mfma_f32_16x16x32_bf16 v[32:35], v[184:187], v[200:203], v[32:35]
	v_mfma_f32_16x16x32_bf16 v[20:23], v[172:175], v[208:211], v[20:23]
	v_mfma_f32_16x16x32_bf16 v[16:19], v[184:187], v[208:211], v[16:19]
	s_setprio 3
	s_barrier
	v_mfma_f32_16x16x32_bf16 v[4:7], v[172:175], v[216:219], v[4:7]
	v_mfma_f32_16x16x32_bf16 v[0:3], v[184:187], v[216:219], v[0:3]
	s_setprio 0
	s_add_i32 s52, 0, 0x18000
	v_add_u32_e32 v155, s52, v149
	s_add_i32 s53, 0, 0x1c000
	ds_read_b128 v[144:147], v155
	ds_read_b128 v[156:159], v155 offset:1024
	ds_read_b128 v[160:163], v155 offset:2048
	ds_read_b128 v[164:167], v155 offset:3072
	v_add_u32_e32 v155, s53, v149
	ds_read_b128 v[168:171], v155
	ds_read_b128 v[172:175], v155 offset:1024
	ds_read_b128 v[176:179], v155 offset:2048
	ds_read_b128 v[184:187], v155 offset:3072
	v_lshl_add_u64 v[224:225], s[28:29], 0, v[128:129]
	s_mov_b32 m0, s34
	v_lshl_add_u64 v[226:227], s[28:29], 0, v[132:133]
	global_load_lds_dwordx4 v[224:225], off
	s_mov_b32 m0, s35
	s_nop 0
	global_load_lds_dwordx4 v[226:227], off
	s_add_u32 s28, s28, 0x40000
	s_addc_u32 s29, s29, 0
	s_mov_b32 m0, s36
	v_lshl_add_u64 v[228:229], s[28:29], 0, v[128:129]
	ds_read_b128 v[188:191], v153 offset:32768
	ds_read_b128 v[192:195], v153 offset:33792
	ds_read_b128 v[196:199], v153 offset:34816
	ds_read_b128 v[200:203], v153 offset:35840
	ds_read_b128 v[204:207], v153 offset:36864
	ds_read_b128 v[208:211], v153 offset:37888
	ds_read_b128 v[212:215], v153 offset:38912
	ds_read_b128 v[216:219], v153 offset:39936
	global_load_lds_dwordx4 v[228:229], off
	v_lshl_add_u64 v[228:229], s[28:29], 0, v[132:133]
	s_mov_b32 m0, s37
	s_nop 0
	global_load_lds_dwordx4 v[228:229], off
	s_waitcnt vmcnt(8)
	s_waitcnt lgkmcnt(0)
	s_barrier
	s_waitcnt lgkmcnt(0)
	v_mfma_f32_16x16x32_bf16 v[124:127], v[144:147], v[188:191], v[124:127]
	v_mfma_f32_16x16x32_bf16 v[120:123], v[160:163], v[188:191], v[120:123]
	v_mfma_f32_16x16x32_bf16 v[108:111], v[144:147], v[196:199], v[108:111]
	v_mfma_f32_16x16x32_bf16 v[104:107], v[160:163], v[196:199], v[104:107]
	v_mfma_f32_16x16x32_bf16 v[92:95], v[144:147], v[204:207], v[92:95]
	v_mfma_f32_16x16x32_bf16 v[88:91], v[160:163], v[204:207], v[88:91]
	v_mfma_f32_16x16x32_bf16 v[76:79], v[144:147], v[212:215], v[76:79]
	v_mfma_f32_16x16x32_bf16 v[72:75], v[160:163], v[212:215], v[72:75]
	v_mfma_f32_16x16x32_bf16 v[124:127], v[156:159], v[192:195], v[124:127]
	v_mfma_f32_16x16x32_bf16 v[120:123], v[164:167], v[192:195], v[120:123]
	v_mfma_f32_16x16x32_bf16 v[108:111], v[156:159], v[200:203], v[108:111]
	v_mfma_f32_16x16x32_bf16 v[104:107], v[164:167], v[200:203], v[104:107]
	v_mfma_f32_16x16x32_bf16 v[92:95], v[156:159], v[208:211], v[92:95]
	v_mfma_f32_16x16x32_bf16 v[88:91], v[164:167], v[208:211], v[88:91]
	v_mfma_f32_16x16x32_bf16 v[76:79], v[156:159], v[216:219], v[76:79]
	v_mfma_f32_16x16x32_bf16 v[72:75], v[164:167], v[216:219], v[72:75]
	v_mfma_f32_16x16x32_bf16 v[116:119], v[168:171], v[188:191], v[116:119]
	v_mfma_f32_16x16x32_bf16 v[112:115], v[176:179], v[188:191], v[112:115]
	v_mfma_f32_16x16x32_bf16 v[100:103], v[168:171], v[196:199], v[100:103]
	v_mfma_f32_16x16x32_bf16 v[96:99], v[176:179], v[196:199], v[96:99]
	v_mfma_f32_16x16x32_bf16 v[84:87], v[168:171], v[204:207], v[84:87]
	v_mfma_f32_16x16x32_bf16 v[80:83], v[176:179], v[204:207], v[80:83]
	v_mfma_f32_16x16x32_bf16 v[68:71], v[168:171], v[212:215], v[68:71]
	v_mfma_f32_16x16x32_bf16 v[64:67], v[176:179], v[212:215], v[64:67]
	v_mfma_f32_16x16x32_bf16 v[116:119], v[172:175], v[192:195], v[116:119]
	v_mfma_f32_16x16x32_bf16 v[112:115], v[184:187], v[192:195], v[112:115]
	v_mfma_f32_16x16x32_bf16 v[100:103], v[172:175], v[200:203], v[100:103]
	v_mfma_f32_16x16x32_bf16 v[96:99], v[184:187], v[200:203], v[96:99]
	v_mfma_f32_16x16x32_bf16 v[84:87], v[172:175], v[208:211], v[84:87]
	v_mfma_f32_16x16x32_bf16 v[80:83], v[184:187], v[208:211], v[80:83]
	s_setprio 3
	s_barrier
	v_mfma_f32_16x16x32_bf16 v[68:71], v[172:175], v[216:219], v[68:71]
	v_mfma_f32_16x16x32_bf16 v[64:67], v[184:187], v[216:219], v[64:67]
	s_setprio 0
	s_add_i32 s28, s52, s33
	v_lshl_add_u64 v[220:221], v[220:221], 0, s[10:11]
	s_mov_b32 m0, s28
	ds_read_b128 v[188:191], v153 offset:49152
	ds_read_b128 v[192:195], v153 offset:50176
	ds_read_b128 v[196:199], v153 offset:51200
	ds_read_b128 v[200:203], v153 offset:52224
	ds_read_b128 v[204:207], v153 offset:53248
	ds_read_b128 v[208:211], v153 offset:54272
	ds_read_b128 v[212:215], v153 offset:55296
	ds_read_b128 v[216:219], v153 offset:56320
	global_load_lds_dwordx4 v[220:221], off
	s_add_i32 m0, s28, 0x2000
	s_add_u32 s26, s26, 0x40080
	v_lshl_add_u64 v[220:221], v[222:223], 0, s[10:11]
	s_addc_u32 s27, s27, 0
	s_add_i32 s28, s53, s33
	global_load_lds_dwordx4 v[220:221], off
	v_lshl_add_u64 v[220:221], s[26:27], 0, v[130:131]
	s_mov_b32 m0, s28
	s_nop 0
	global_load_lds_dwordx4 v[220:221], off
	v_lshl_add_u64 v[220:221], s[26:27], 0, v[134:135]
	s_add_i32 m0, s28, 0x2000
	s_nop 0
	global_load_lds_dwordx4 v[220:221], off
	s_waitcnt vmcnt(6)
	s_waitcnt lgkmcnt(0)
	s_barrier
	s_waitcnt lgkmcnt(0)
	v_mfma_f32_16x16x32_bf16 v[60:63], v[144:147], v[188:191], v[60:63]
	v_mfma_f32_16x16x32_bf16 v[56:59], v[160:163], v[188:191], v[56:59]
	v_mfma_f32_16x16x32_bf16 v[44:47], v[144:147], v[196:199], v[44:47]
	v_mfma_f32_16x16x32_bf16 v[40:43], v[160:163], v[196:199], v[40:43]
	v_mfma_f32_16x16x32_bf16 v[28:31], v[144:147], v[204:207], v[28:31]
	v_mfma_f32_16x16x32_bf16 v[24:27], v[160:163], v[204:207], v[24:27]
	v_mfma_f32_16x16x32_bf16 v[12:15], v[144:147], v[212:215], v[12:15]
	v_mfma_f32_16x16x32_bf16 v[8:11], v[160:163], v[212:215], v[8:11]
	v_mfma_f32_16x16x32_bf16 v[60:63], v[156:159], v[192:195], v[60:63]
	v_mfma_f32_16x16x32_bf16 v[56:59], v[164:167], v[192:195], v[56:59]
	v_mfma_f32_16x16x32_bf16 v[44:47], v[156:159], v[200:203], v[44:47]
	v_mfma_f32_16x16x32_bf16 v[40:43], v[164:167], v[200:203], v[40:43]
	v_mfma_f32_16x16x32_bf16 v[28:31], v[156:159], v[208:211], v[28:31]
	v_mfma_f32_16x16x32_bf16 v[24:27], v[164:167], v[208:211], v[24:27]
	v_mfma_f32_16x16x32_bf16 v[12:15], v[156:159], v[216:219], v[12:15]
	v_mfma_f32_16x16x32_bf16 v[8:11], v[164:167], v[216:219], v[8:11]
	v_mfma_f32_16x16x32_bf16 v[52:55], v[168:171], v[188:191], v[52:55]
	v_mfma_f32_16x16x32_bf16 v[48:51], v[176:179], v[188:191], v[48:51]
	v_mfma_f32_16x16x32_bf16 v[36:39], v[168:171], v[196:199], v[36:39]
	v_mfma_f32_16x16x32_bf16 v[32:35], v[176:179], v[196:199], v[32:35]
	v_mfma_f32_16x16x32_bf16 v[20:23], v[168:171], v[204:207], v[20:23]
	v_mfma_f32_16x16x32_bf16 v[16:19], v[176:179], v[204:207], v[16:19]
	v_mfma_f32_16x16x32_bf16 v[4:7], v[168:171], v[212:215], v[4:7]
	v_mfma_f32_16x16x32_bf16 v[0:3], v[176:179], v[212:215], v[0:3]
	v_mfma_f32_16x16x32_bf16 v[52:55], v[172:175], v[192:195], v[52:55]
	v_mfma_f32_16x16x32_bf16 v[48:51], v[184:187], v[192:195], v[48:51]
	v_mfma_f32_16x16x32_bf16 v[36:39], v[172:175], v[200:203], v[36:39]
	v_mfma_f32_16x16x32_bf16 v[32:35], v[184:187], v[200:203], v[32:35]
	v_mfma_f32_16x16x32_bf16 v[20:23], v[172:175], v[208:211], v[20:23]
	v_mfma_f32_16x16x32_bf16 v[16:19], v[184:187], v[208:211], v[16:19]
	s_setprio 3
	s_barrier
	v_mfma_f32_16x16x32_bf16 v[4:7], v[172:175], v[216:219], v[4:7]
	v_mfma_f32_16x16x32_bf16 v[0:3], v[184:187], v[216:219], v[0:3]
	s_setprio 0
	v_lshl_add_u64 v[220:221], v[224:225], 0, s[10:11]
	s_mov_b32 m0, s39
	s_nop 0
	global_load_lds_dwordx4 v[220:221], off
	v_lshl_add_u64 v[220:221], v[226:227], 0, s[10:11]
	s_mov_b32 m0, s40
	s_nop 0
	global_load_lds_dwordx4 v[220:221], off
	s_add_i32 s51, s51, 2
	s_add_u32 s24, s24, 0x100
	s_addc_u32 s25, s25, 0
	s_add_u32 s47, s47, 0x100
	s_addc_u32 s50, s50, 0
	s_cmp_gt_u32 s51, 13

.LBB0_704:
	s_ashr_i32 s13, s12, 31
	s_lshl_b64 s[14:15], s[12:13], 19
	s_add_u32 s14, s74, s14
	s_addc_u32 s15, s75, s15
	s_add_u32 s98, s20, 0x700
	s_addc_u32 s99, s21, 0
	s_and_b64 s[16:17], s[0:1], exec
	s_cselect_b32 s13, s15, s99
	s_cselect_b32 s42, s14, s98
	s_ashr_i32 s11, s10, 31
	s_lshl_b64 s[16:17], s[10:11], 19
	s_add_u32 s16, s26, s16
	s_addc_u32 s17, s27, s17
	s_add_u32 s98, s22, 0x700
	s_addc_u32 s99, s23, 0
	s_and_b64 s[24:25], s[0:1], exec
	s_cselect_b32 s11, s17, s99
	s_cselect_b32 s43, s16, s98
	s_add_u32 s20, s20, 0x40080
	s_addc_u32 s21, s21, 0
	s_add_u32 s46, s22, 0x100
	s_addc_u32 s47, s23, 0
	s_mov_b32 s50, -2
	ds_read_b128 v[154:157], v151
	ds_read_b128 v[158:161], v151 offset:1024
	ds_read_b128 v[162:165], v151 offset:2048
	ds_read_b128 v[166:169], v151 offset:3072
	ds_read_b128 v[170:173], v152
	ds_read_b128 v[174:177], v152 offset:1024
	ds_read_b128 v[184:187], v152 offset:2048
	ds_read_b128 v[188:191], v152 offset:3072
	s_add_u32 s22, s20, 0xfffc0080
	s_addc_u32 s23, s21, -1
	s_cmp_eq_u32 s50, 12
	s_cselect_b32 s25, s13, s23
	s_cselect_b32 s24, s42, s22
	s_cselect_b32 s23, s11, s47
	s_cselect_b32 s22, s43, s46
	v_lshl_add_u64 v[178:179], s[20:21], 0, v[136:137]
	s_add_i32 m0, s19, 0xc000
	ds_read_b128 v[192:195], v153
	ds_read_b128 v[196:199], v153 offset:1024
	ds_read_b128 v[200:203], v153 offset:2048
	ds_read_b128 v[204:207], v153 offset:3072
	ds_read_b128 v[208:211], v153 offset:4096
	ds_read_b128 v[212:215], v153 offset:5120
	ds_read_b128 v[216:219], v153 offset:6144
	ds_read_b128 v[220:223], v153 offset:7168
	global_load_lds_dwordx4 v[178:179], off
	v_lshl_add_u64 v[178:179], s[20:21], 0, v[138:139]
	s_add_i32 m0, s19, 0xe000
	s_nop 0
	global_load_lds_dwordx4 v[178:179], off
	s_waitcnt vmcnt(8)
	s_waitcnt lgkmcnt(0)
	s_barrier
	s_waitcnt lgkmcnt(0)
	v_mfma_f32_16x16x32_bf16 v[124:127], v[154:157], v[192:195], 0
	v_mfma_f32_16x16x32_bf16 v[116:119], v[162:165], v[192:195], 0
	v_mfma_f32_16x16x32_bf16 v[108:111], v[154:157], v[200:203], 0
	v_mfma_f32_16x16x32_bf16 v[100:103], v[162:165], v[200:203], 0
	v_mfma_f32_16x16x32_bf16 v[92:95], v[154:157], v[208:211], 0
	v_mfma_f32_16x16x32_bf16 v[84:87], v[162:165], v[208:211], 0
	v_mfma_f32_16x16x32_bf16 v[76:79], v[154:157], v[216:219], 0
	v_mfma_f32_16x16x32_bf16 v[68:71], v[162:165], v[216:219], 0
	v_mfma_f32_16x16x32_bf16 v[124:127], v[158:161], v[196:199], v[124:127]
	v_mfma_f32_16x16x32_bf16 v[116:119], v[166:169], v[196:199], v[116:119]
	v_mfma_f32_16x16x32_bf16 v[108:111], v[158:161], v[204:207], v[108:111]
	v_mfma_f32_16x16x32_bf16 v[100:103], v[166:169], v[204:207], v[100:103]
	v_mfma_f32_16x16x32_bf16 v[92:95], v[158:161], v[212:215], v[92:95]
	v_mfma_f32_16x16x32_bf16 v[84:87], v[166:169], v[212:215], v[84:87]
	v_mfma_f32_16x16x32_bf16 v[76:79], v[158:161], v[220:223], v[76:79]
	v_mfma_f32_16x16x32_bf16 v[68:71], v[166:169], v[220:223], v[68:71]
	v_mfma_f32_16x16x32_bf16 v[120:123], v[170:173], v[192:195], 0
	v_mfma_f32_16x16x32_bf16 v[112:115], v[184:187], v[192:195], 0
	v_mfma_f32_16x16x32_bf16 v[104:107], v[170:173], v[200:203], 0
	v_mfma_f32_16x16x32_bf16 v[96:99], v[184:187], v[200:203], 0
	v_mfma_f32_16x16x32_bf16 v[88:91], v[170:173], v[208:211], 0
	v_mfma_f32_16x16x32_bf16 v[80:83], v[184:187], v[208:211], 0
	v_mfma_f32_16x16x32_bf16 v[72:75], v[170:173], v[216:219], 0
	v_mfma_f32_16x16x32_bf16 v[64:67], v[184:187], v[216:219], 0
	v_mfma_f32_16x16x32_bf16 v[120:123], v[174:177], v[196:199], v[120:123]
	v_mfma_f32_16x16x32_bf16 v[112:115], v[188:191], v[196:199], v[112:115]
	v_mfma_f32_16x16x32_bf16 v[104:107], v[174:177], v[204:207], v[104:107]
	v_mfma_f32_16x16x32_bf16 v[96:99], v[188:191], v[204:207], v[96:99]
	v_mfma_f32_16x16x32_bf16 v[88:91], v[174:177], v[212:215], v[88:91]
	v_mfma_f32_16x16x32_bf16 v[80:83], v[188:191], v[212:215], v[80:83]
	s_setprio 3
	s_barrier
	v_mfma_f32_16x16x32_bf16 v[72:75], v[174:177], v[220:223], v[72:75]
	v_mfma_f32_16x16x32_bf16 v[64:67], v[188:191], v[220:223], v[64:67]
	s_setprio 0
	s_add_i32 s51, s36, s28
	v_lshl_add_u64 v[178:179], s[22:23], 0, v[132:133]
	s_mov_b32 m0, s51
	ds_read_b128 v[192:195], v153 offset:16384
	ds_read_b128 v[196:199], v153 offset:17408
	ds_read_b128 v[200:203], v153 offset:18432
	ds_read_b128 v[204:207], v153 offset:19456
	ds_read_b128 v[208:211], v153 offset:20480
	ds_read_b128 v[212:215], v153 offset:21504
	ds_read_b128 v[216:219], v153 offset:22528
	ds_read_b128 v[220:223], v153 offset:23552
	global_load_lds_dwordx4 v[178:179], off
	s_add_i32 m0, s51, 0x2000
	s_add_u32 s52, s22, 0x40000
	v_lshl_add_u64 v[224:225], s[22:23], 0, v[128:129]
	s_addc_u32 s53, s23, 0
	s_add_i32 s51, s37, s28
	global_load_lds_dwordx4 v[224:225], off
	v_lshl_add_u64 v[226:227], s[52:53], 0, v[132:133]
	s_mov_b32 m0, s51
	global_load_lds_dwordx4 v[226:227], off
	v_lshl_add_u64 v[226:227], s[52:53], 0, v[128:129]
	s_add_i32 m0, s51, 0x2000
	s_nop 0
	global_load_lds_dwordx4 v[226:227], off
	s_waitcnt vmcnt(6)
	s_waitcnt lgkmcnt(0)
	s_barrier
	s_waitcnt lgkmcnt(0)
	v_mfma_f32_16x16x32_bf16 v[60:63], v[154:157], v[192:195], 0
	v_mfma_f32_16x16x32_bf16 v[52:55], v[162:165], v[192:195], 0
	v_mfma_f32_16x16x32_bf16 v[44:47], v[154:157], v[200:203], 0
	v_mfma_f32_16x16x32_bf16 v[36:39], v[162:165], v[200:203], 0
	v_mfma_f32_16x16x32_bf16 v[28:31], v[154:157], v[208:211], 0
	v_mfma_f32_16x16x32_bf16 v[20:23], v[162:165], v[208:211], 0
	v_mfma_f32_16x16x32_bf16 v[12:15], v[154:157], v[216:219], 0
	v_mfma_f32_16x16x32_bf16 v[4:7], v[162:165], v[216:219], 0
	v_mfma_f32_16x16x32_bf16 v[60:63], v[158:161], v[196:199], v[60:63]
	v_mfma_f32_16x16x32_bf16 v[52:55], v[166:169], v[196:199], v[52:55]
	v_mfma_f32_16x16x32_bf16 v[44:47], v[158:161], v[204:207], v[44:47]
	v_mfma_f32_16x16x32_bf16 v[36:39], v[166:169], v[204:207], v[36:39]
	v_mfma_f32_16x16x32_bf16 v[28:31], v[158:161], v[212:215], v[28:31]
	v_mfma_f32_16x16x32_bf16 v[20:23], v[166:169], v[212:215], v[20:23]
	v_mfma_f32_16x16x32_bf16 v[12:15], v[158:161], v[220:223], v[12:15]
	v_mfma_f32_16x16x32_bf16 v[4:7], v[166:169], v[220:223], v[4:7]
	v_mfma_f32_16x16x32_bf16 v[56:59], v[170:173], v[192:195], 0
	v_mfma_f32_16x16x32_bf16 v[48:51], v[184:187], v[192:195], 0
	v_mfma_f32_16x16x32_bf16 v[40:43], v[170:173], v[200:203], 0
	v_mfma_f32_16x16x32_bf16 v[32:35], v[184:187], v[200:203], 0
	v_mfma_f32_16x16x32_bf16 v[24:27], v[170:173], v[208:211], 0
	v_mfma_f32_16x16x32_bf16 v[16:19], v[184:187], v[208:211], 0
	v_mfma_f32_16x16x32_bf16 v[8:11], v[170:173], v[216:219], 0
	v_mfma_f32_16x16x32_bf16 v[0:3], v[184:187], v[216:219], 0
	v_mfma_f32_16x16x32_bf16 v[56:59], v[174:177], v[196:199], v[56:59]
	v_mfma_f32_16x16x32_bf16 v[48:51], v[188:191], v[196:199], v[48:51]
	v_mfma_f32_16x16x32_bf16 v[40:43], v[174:177], v[204:207], v[40:43]
	v_mfma_f32_16x16x32_bf16 v[32:35], v[188:191], v[204:207], v[32:35]
	v_mfma_f32_16x16x32_bf16 v[24:27], v[174:177], v[212:215], v[24:27]
	v_mfma_f32_16x16x32_bf16 v[16:19], v[188:191], v[212:215], v[16:19]
	s_setprio 3
	s_barrier
	v_mfma_f32_16x16x32_bf16 v[8:11], v[174:177], v[220:223], v[8:11]
	v_mfma_f32_16x16x32_bf16 v[0:3], v[188:191], v[220:223], v[0:3]
	s_setprio 0
	s_add_i32 s51, 0, 0x18000
	s_add_i32 s52, 0, 0x1c000
	v_add_u32_e32 v166, s51, v145
	v_add_u32_e32 v180, s52, v145
	ds_read_b128 v[154:157], v166
	ds_read_b128 v[158:161], v166 offset:1024
	ds_read_b128 v[162:165], v166 offset:2048
	ds_read_b128 v[166:169], v166 offset:3072
	ds_read_b128 v[170:173], v180
	ds_read_b128 v[174:177], v180 offset:1024
	ds_read_b128 v[184:187], v180 offset:2048
	ds_read_b128 v[188:191], v180 offset:3072
	v_lshl_add_u64 v[226:227], s[24:25], 0, v[134:135]
	s_mov_b32 m0, s19
	v_lshl_add_u64 v[228:229], s[24:25], 0, v[130:131]
	global_load_lds_dwordx4 v[226:227], off
	s_mov_b32 m0, s30
	s_nop 0
	global_load_lds_dwordx4 v[228:229], off
	s_add_u32 s24, s24, 0x40000
	s_addc_u32 s25, s25, 0
	s_mov_b32 m0, s31
	v_lshl_add_u64 v[230:231], s[24:25], 0, v[134:135]
	ds_read_b128 v[192:195], v153 offset:32768
	ds_read_b128 v[196:199], v153 offset:33792
	ds_read_b128 v[200:203], v153 offset:34816
	ds_read_b128 v[204:207], v153 offset:35840
	ds_read_b128 v[208:211], v153 offset:36864
	ds_read_b128 v[212:215], v153 offset:37888
	ds_read_b128 v[216:219], v153 offset:38912
	ds_read_b128 v[220:223], v153 offset:39936
	global_load_lds_dwordx4 v[230:231], off
	v_lshl_add_u64 v[230:231], s[24:25], 0, v[130:131]
	s_mov_b32 m0, s33
	s_nop 0
	global_load_lds_dwordx4 v[230:231], off
	s_waitcnt vmcnt(8)
	s_waitcnt lgkmcnt(0)
	s_barrier
	s_waitcnt lgkmcnt(0)
	v_mfma_f32_16x16x32_bf16 v[124:127], v[154:157], v[192:195], v[124:127]
	v_mfma_f32_16x16x32_bf16 v[116:119], v[162:165], v[192:195], v[116:119]
	v_mfma_f32_16x16x32_bf16 v[108:111], v[154:157], v[200:203], v[108:111]
	v_mfma_f32_16x16x32_bf16 v[100:103], v[162:165], v[200:203], v[100:103]
	v_mfma_f32_16x16x32_bf16 v[92:95], v[154:157], v[208:211], v[92:95]
	v_mfma_f32_16x16x32_bf16 v[84:87], v[162:165], v[208:211], v[84:87]
	v_mfma_f32_16x16x32_bf16 v[76:79], v[154:157], v[216:219], v[76:79]
	v_mfma_f32_16x16x32_bf16 v[68:71], v[162:165], v[216:219], v[68:71]
	v_mfma_f32_16x16x32_bf16 v[124:127], v[158:161], v[196:199], v[124:127]
	v_mfma_f32_16x16x32_bf16 v[116:119], v[166:169], v[196:199], v[116:119]
	v_mfma_f32_16x16x32_bf16 v[108:111], v[158:161], v[204:207], v[108:111]
	v_mfma_f32_16x16x32_bf16 v[100:103], v[166:169], v[204:207], v[100:103]
	v_mfma_f32_16x16x32_bf16 v[92:95], v[158:161], v[212:215], v[92:95]
	v_mfma_f32_16x16x32_bf16 v[84:87], v[166:169], v[212:215], v[84:87]
	v_mfma_f32_16x16x32_bf16 v[76:79], v[158:161], v[220:223], v[76:79]
	v_mfma_f32_16x16x32_bf16 v[68:71], v[166:169], v[220:223], v[68:71]
	v_mfma_f32_16x16x32_bf16 v[120:123], v[170:173], v[192:195], v[120:123]
	v_mfma_f32_16x16x32_bf16 v[112:115], v[184:187], v[192:195], v[112:115]
	v_mfma_f32_16x16x32_bf16 v[104:107], v[170:173], v[200:203], v[104:107]
	v_mfma_f32_16x16x32_bf16 v[96:99], v[184:187], v[200:203], v[96:99]
	v_mfma_f32_16x16x32_bf16 v[88:91], v[170:173], v[208:211], v[88:91]
	v_mfma_f32_16x16x32_bf16 v[80:83], v[184:187], v[208:211], v[80:83]
	v_mfma_f32_16x16x32_bf16 v[72:75], v[170:173], v[216:219], v[72:75]
	v_mfma_f32_16x16x32_bf16 v[64:67], v[184:187], v[216:219], v[64:67]
	v_mfma_f32_16x16x32_bf16 v[120:123], v[174:177], v[196:199], v[120:123]
	v_mfma_f32_16x16x32_bf16 v[112:115], v[188:191], v[196:199], v[112:115]
	v_mfma_f32_16x16x32_bf16 v[104:107], v[174:177], v[204:207], v[104:107]
	v_mfma_f32_16x16x32_bf16 v[96:99], v[188:191], v[204:207], v[96:99]
	v_mfma_f32_16x16x32_bf16 v[88:91], v[174:177], v[212:215], v[88:91]
	v_mfma_f32_16x16x32_bf16 v[80:83], v[188:191], v[212:215], v[80:83]
	s_setprio 3
	s_barrier
	v_mfma_f32_16x16x32_bf16 v[72:75], v[174:177], v[220:223], v[72:75]
	v_mfma_f32_16x16x32_bf16 v[64:67], v[188:191], v[220:223], v[64:67]
	s_setprio 0
	s_add_i32 s24, s51, s28
	v_lshl_add_u64 v[178:179], v[178:179], 0, s[6:7]
	s_mov_b32 m0, s24
	ds_read_b128 v[192:195], v153 offset:49152
	ds_read_b128 v[196:199], v153 offset:50176
	ds_read_b128 v[200:203], v153 offset:51200
	ds_read_b128 v[204:207], v153 offset:52224
	ds_read_b128 v[208:211], v153 offset:53248
	ds_read_b128 v[212:215], v153 offset:54272
	ds_read_b128 v[216:219], v153 offset:55296
	ds_read_b128 v[220:223], v153 offset:56320
	global_load_lds_dwordx4 v[178:179], off
	s_add_i32 m0, s24, 0x2000
	s_add_u32 s22, s22, 0x40080
	v_lshl_add_u64 v[178:179], v[224:225], 0, s[6:7]
	s_addc_u32 s23, s23, 0
	s_add_i32 s24, s52, s28
	global_load_lds_dwordx4 v[178:179], off
	v_lshl_add_u64 v[178:179], s[22:23], 0, v[132:133]
	s_mov_b32 m0, s24
	s_nop 0
	global_load_lds_dwordx4 v[178:179], off
	v_lshl_add_u64 v[178:179], s[22:23], 0, v[128:129]
	s_add_i32 m0, s24, 0x2000
	s_nop 0
	global_load_lds_dwordx4 v[178:179], off
	s_waitcnt vmcnt(6)
	s_waitcnt lgkmcnt(0)
	s_barrier
	s_waitcnt lgkmcnt(0)
	v_mfma_f32_16x16x32_bf16 v[60:63], v[154:157], v[192:195], v[60:63]
	v_mfma_f32_16x16x32_bf16 v[52:55], v[162:165], v[192:195], v[52:55]
	v_mfma_f32_16x16x32_bf16 v[44:47], v[154:157], v[200:203], v[44:47]
	v_mfma_f32_16x16x32_bf16 v[36:39], v[162:165], v[200:203], v[36:39]
	v_mfma_f32_16x16x32_bf16 v[28:31], v[154:157], v[208:211], v[28:31]
	v_mfma_f32_16x16x32_bf16 v[20:23], v[162:165], v[208:211], v[20:23]
	v_mfma_f32_16x16x32_bf16 v[12:15], v[154:157], v[216:219], v[12:15]
	v_mfma_f32_16x16x32_bf16 v[4:7], v[162:165], v[216:219], v[4:7]
	v_mfma_f32_16x16x32_bf16 v[60:63], v[158:161], v[196:199], v[60:63]
	v_mfma_f32_16x16x32_bf16 v[52:55], v[166:169], v[196:199], v[52:55]
	v_mfma_f32_16x16x32_bf16 v[44:47], v[158:161], v[204:207], v[44:47]
	v_mfma_f32_16x16x32_bf16 v[36:39], v[166:169], v[204:207], v[36:39]
	v_mfma_f32_16x16x32_bf16 v[28:31], v[158:161], v[212:215], v[28:31]
	v_mfma_f32_16x16x32_bf16 v[20:23], v[166:169], v[212:215], v[20:23]
	v_mfma_f32_16x16x32_bf16 v[12:15], v[158:161], v[220:223], v[12:15]
	v_mfma_f32_16x16x32_bf16 v[4:7], v[166:169], v[220:223], v[4:7]
	v_mfma_f32_16x16x32_bf16 v[56:59], v[170:173], v[192:195], v[56:59]
	v_mfma_f32_16x16x32_bf16 v[48:51], v[184:187], v[192:195], v[48:51]
	v_mfma_f32_16x16x32_bf16 v[40:43], v[170:173], v[200:203], v[40:43]
	v_mfma_f32_16x16x32_bf16 v[32:35], v[184:187], v[200:203], v[32:35]
	v_mfma_f32_16x16x32_bf16 v[24:27], v[170:173], v[208:211], v[24:27]
	v_mfma_f32_16x16x32_bf16 v[16:19], v[184:187], v[208:211], v[16:19]
	v_mfma_f32_16x16x32_bf16 v[8:11], v[170:173], v[216:219], v[8:11]
	v_mfma_f32_16x16x32_bf16 v[0:3], v[184:187], v[216:219], v[0:3]
	v_mfma_f32_16x16x32_bf16 v[56:59], v[174:177], v[196:199], v[56:59]
	v_mfma_f32_16x16x32_bf16 v[48:51], v[188:191], v[196:199], v[48:51]
	v_mfma_f32_16x16x32_bf16 v[40:43], v[174:177], v[204:207], v[40:43]
	v_mfma_f32_16x16x32_bf16 v[32:35], v[188:191], v[204:207], v[32:35]
	v_mfma_f32_16x16x32_bf16 v[24:27], v[174:177], v[212:215], v[24:27]
	v_mfma_f32_16x16x32_bf16 v[16:19], v[188:191], v[212:215], v[16:19]
	s_setprio 3
	s_barrier
	v_mfma_f32_16x16x32_bf16 v[8:11], v[174:177], v[220:223], v[8:11]
	v_mfma_f32_16x16x32_bf16 v[0:3], v[188:191], v[220:223], v[0:3]
	s_setprio 0
	v_lshl_add_u64 v[178:179], v[226:227], 0, s[6:7]
	s_mov_b32 m0, s34
	s_nop 0
	global_load_lds_dwordx4 v[178:179], off
	v_lshl_add_u64 v[178:179], v[228:229], 0, s[6:7]
	s_mov_b32 m0, s35
	s_nop 0
	global_load_lds_dwordx4 v[178:179], off
	s_add_i32 s50, s50, 2
	s_add_u32 s20, s20, 0x100
	s_addc_u32 s21, s21, 0
	s_add_u32 s46, s46, 0x100
	s_addc_u32 s47, s47, 0
	s_cmp_gt_u32 s50, 13

.LBB0_782:
	s_nop 0
	v_cndmask_b32_e64 v0, 0, 1, s[6:7]
	v_cmp_ne_u32_e64 s[4:5], 1, v0
	s_andn2_b64 vcc, exec, s[6:7]
	s_add_u32 s6, s18, 0x1500
	s_addc_u32 s7, s19, 0
	s_cbranch_vccnz .LBB0_784
	s_mul_i32 s6, s41, 0x160000
	s_mul_hi_i32 s7, s41, 0x160000
	s_add_u32 s6, s76, s6
	s_addc_u32 s7, s77, s7
.LBB0_784:
	s_and_b64 vcc, exec, s[4:5]
	s_add_u32 s16, s20, 0x1500
	s_addc_u32 s17, s21, 0
	s_cbranch_vccnz .LBB0_786
	s_mul_i32 s16, s40, 0x160000
	s_mul_hi_i32 s17, s40, 0x160000
	s_add_u32 s16, s26, s16
	s_addc_u32 s17, s27, s17

.LBB0_876:
	s_ashr_i32 s23, s22, 31
	s_lshl_b64 s[24:25], s[22:23], 19
	s_add_u32 s24, s74, s24
	s_addc_u32 s25, s75, s25
	s_add_u32 s98, s28, 0x700
	s_addc_u32 s99, s29, 0
	s_and_b64 s[26:27], s[6:7], exec
	s_cselect_b32 s11, s25, s99
	s_cselect_b32 s23, s24, s98
	s_ashr_i32 s21, s20, 31
	s_lshl_b64 s[26:27], s[20:21], 19
	s_add_u32 s26, s33, s26
	s_addc_u32 s27, s36, s27
	s_add_u32 s98, s30, 0x700
	s_addc_u32 s99, s31, 0
	s_and_b64 s[34:35], s[6:7], exec
	s_cselect_b32 s21, s27, s99
	s_cselect_b32 s53, s26, s98
	s_add_u32 s28, s28, 0x40080
	s_addc_u32 s29, s29, 0
	s_add_u32 s54, s30, 0x100
	s_addc_u32 s55, s31, 0
	s_mov_b32 s56, -2
	s_waitcnt lgkmcnt(0)
	ds_read_b128 v[144:147], v173
	ds_read_b128 v[148:151], v173 offset:1024
	ds_read_b128 v[152:155], v173 offset:2048
	ds_read_b128 v[156:159], v173 offset:3072
	ds_read_b128 v[184:187], v174
	ds_read_b128 v[188:191], v174 offset:1024
	ds_read_b128 v[192:195], v174 offset:2048
	ds_read_b128 v[196:199], v174 offset:3072
	s_add_u32 s30, s28, 0xfffc0080
	s_addc_u32 s31, s29, -1
	s_cmp_eq_u32 s56, 12
	s_cselect_b32 s35, s11, s31
	s_cselect_b32 s34, s23, s30
	s_cselect_b32 s31, s21, s55
	s_cselect_b32 s30, s53, s54
	v_lshl_add_u64 v[160:161], s[28:29], 0, v[136:137]
	s_add_i32 m0, s38, 0xc000
	ds_read_b128 v[200:203], v175
	ds_read_b128 v[204:207], v175 offset:1024
	ds_read_b128 v[208:211], v175 offset:2048
	ds_read_b128 v[212:215], v175 offset:3072
	ds_read_b128 v[216:219], v175 offset:4096
	ds_read_b128 v[220:223], v175 offset:5120
	ds_read_b128 v[224:227], v175 offset:6144
	ds_read_b128 v[228:231], v175 offset:7168
	global_load_lds_dwordx4 v[160:161], off
	v_lshl_add_u64 v[160:161], s[28:29], 0, v[138:139]
	s_add_i32 m0, s38, 0xe000
	s_nop 0
	global_load_lds_dwordx4 v[160:161], off
	s_waitcnt vmcnt(8)
	s_waitcnt lgkmcnt(0)
	s_barrier
	s_waitcnt lgkmcnt(0)
	v_mfma_f32_16x16x32_bf16 v[124:127], v[144:147], v[200:203], 0
	v_mfma_f32_16x16x32_bf16 v[120:123], v[152:155], v[200:203], 0
	v_mfma_f32_16x16x32_bf16 v[108:111], v[144:147], v[208:211], 0
	v_mfma_f32_16x16x32_bf16 v[104:107], v[152:155], v[208:211], 0
	v_mfma_f32_16x16x32_bf16 v[92:95], v[144:147], v[216:219], 0
	v_mfma_f32_16x16x32_bf16 v[88:91], v[152:155], v[216:219], 0
	v_mfma_f32_16x16x32_bf16 v[76:79], v[144:147], v[224:227], 0
	v_mfma_f32_16x16x32_bf16 v[72:75], v[152:155], v[224:227], 0
	v_mfma_f32_16x16x32_bf16 v[124:127], v[148:151], v[204:207], v[124:127]
	v_mfma_f32_16x16x32_bf16 v[120:123], v[156:159], v[204:207], v[120:123]
	v_mfma_f32_16x16x32_bf16 v[108:111], v[148:151], v[212:215], v[108:111]
	v_mfma_f32_16x16x32_bf16 v[104:107], v[156:159], v[212:215], v[104:107]
	v_mfma_f32_16x16x32_bf16 v[92:95], v[148:151], v[220:223], v[92:95]
	v_mfma_f32_16x16x32_bf16 v[88:91], v[156:159], v[220:223], v[88:91]
	v_mfma_f32_16x16x32_bf16 v[76:79], v[148:151], v[228:231], v[76:79]
	v_mfma_f32_16x16x32_bf16 v[72:75], v[156:159], v[228:231], v[72:75]
	v_mfma_f32_16x16x32_bf16 v[116:119], v[184:187], v[200:203], 0
	v_mfma_f32_16x16x32_bf16 v[112:115], v[192:195], v[200:203], 0
	v_mfma_f32_16x16x32_bf16 v[100:103], v[184:187], v[208:211], 0
	v_mfma_f32_16x16x32_bf16 v[96:99], v[192:195], v[208:211], 0
	v_mfma_f32_16x16x32_bf16 v[84:87], v[184:187], v[216:219], 0
	v_mfma_f32_16x16x32_bf16 v[80:83], v[192:195], v[216:219], 0
	v_mfma_f32_16x16x32_bf16 v[68:71], v[184:187], v[224:227], 0
	v_mfma_f32_16x16x32_bf16 v[64:67], v[192:195], v[224:227], 0
	v_mfma_f32_16x16x32_bf16 v[116:119], v[188:191], v[204:207], v[116:119]
	v_mfma_f32_16x16x32_bf16 v[112:115], v[196:199], v[204:207], v[112:115]
	v_mfma_f32_16x16x32_bf16 v[100:103], v[188:191], v[212:215], v[100:103]
	v_mfma_f32_16x16x32_bf16 v[96:99], v[196:199], v[212:215], v[96:99]
	v_mfma_f32_16x16x32_bf16 v[84:87], v[188:191], v[220:223], v[84:87]
	v_mfma_f32_16x16x32_bf16 v[80:83], v[196:199], v[220:223], v[80:83]
	s_setprio 3
	s_barrier
	v_mfma_f32_16x16x32_bf16 v[68:71], v[188:191], v[228:231], v[68:71]
	v_mfma_f32_16x16x32_bf16 v[64:67], v[196:199], v[228:231], v[64:67]
	s_setprio 0
	s_add_i32 s57, s47, s37
	v_lshl_add_u64 v[160:161], s[30:31], 0, v[130:131]
	s_mov_b32 m0, s57
	ds_read_b128 v[200:203], v175 offset:16384
	ds_read_b128 v[204:207], v175 offset:17408
	ds_read_b128 v[208:211], v175 offset:18432
	ds_read_b128 v[212:215], v175 offset:19456
	ds_read_b128 v[216:219], v175 offset:20480
	ds_read_b128 v[220:223], v175 offset:21504
	ds_read_b128 v[224:227], v175 offset:22528
	ds_read_b128 v[228:231], v175 offset:23552
	global_load_lds_dwordx4 v[160:161], off
	s_add_i32 m0, s57, 0x2000
	s_add_u32 s58, s30, 0x40000
	v_lshl_add_u64 v[178:179], s[30:31], 0, v[134:135]
	s_addc_u32 s59, s31, 0
	s_add_i32 s57, s50, s37
	global_load_lds_dwordx4 v[178:179], off
	v_lshl_add_u64 v[232:233], s[58:59], 0, v[130:131]
	s_mov_b32 m0, s57
	global_load_lds_dwordx4 v[232:233], off
	v_lshl_add_u64 v[232:233], s[58:59], 0, v[134:135]
	s_add_i32 m0, s57, 0x2000
	s_nop 0
	global_load_lds_dwordx4 v[232:233], off
	s_waitcnt vmcnt(6)
	s_waitcnt lgkmcnt(0)
	s_barrier
	s_waitcnt lgkmcnt(0)
	v_mfma_f32_16x16x32_bf16 v[60:63], v[144:147], v[200:203], 0
	v_mfma_f32_16x16x32_bf16 v[56:59], v[152:155], v[200:203], 0
	v_mfma_f32_16x16x32_bf16 v[44:47], v[144:147], v[208:211], 0
	v_mfma_f32_16x16x32_bf16 v[40:43], v[152:155], v[208:211], 0
	v_mfma_f32_16x16x32_bf16 v[28:31], v[144:147], v[216:219], 0
	v_mfma_f32_16x16x32_bf16 v[24:27], v[152:155], v[216:219], 0
	v_mfma_f32_16x16x32_bf16 v[12:15], v[144:147], v[224:227], 0
	v_mfma_f32_16x16x32_bf16 v[8:11], v[152:155], v[224:227], 0
	v_mfma_f32_16x16x32_bf16 v[60:63], v[148:151], v[204:207], v[60:63]
	v_mfma_f32_16x16x32_bf16 v[56:59], v[156:159], v[204:207], v[56:59]
	v_mfma_f32_16x16x32_bf16 v[44:47], v[148:151], v[212:215], v[44:47]
	v_mfma_f32_16x16x32_bf16 v[40:43], v[156:159], v[212:215], v[40:43]
	v_mfma_f32_16x16x32_bf16 v[28:31], v[148:151], v[220:223], v[28:31]
	v_mfma_f32_16x16x32_bf16 v[24:27], v[156:159], v[220:223], v[24:27]
	v_mfma_f32_16x16x32_bf16 v[12:15], v[148:151], v[228:231], v[12:15]
	v_mfma_f32_16x16x32_bf16 v[8:11], v[156:159], v[228:231], v[8:11]
	v_mfma_f32_16x16x32_bf16 v[52:55], v[184:187], v[200:203], 0
	v_mfma_f32_16x16x32_bf16 v[48:51], v[192:195], v[200:203], 0
	v_mfma_f32_16x16x32_bf16 v[36:39], v[184:187], v[208:211], 0
	v_mfma_f32_16x16x32_bf16 v[32:35], v[192:195], v[208:211], 0
	v_mfma_f32_16x16x32_bf16 v[20:23], v[184:187], v[216:219], 0
	v_mfma_f32_16x16x32_bf16 v[16:19], v[192:195], v[216:219], 0
	v_mfma_f32_16x16x32_bf16 v[4:7], v[184:187], v[224:227], 0
	v_mfma_f32_16x16x32_bf16 v[0:3], v[192:195], v[224:227], 0
	v_mfma_f32_16x16x32_bf16 v[52:55], v[188:191], v[204:207], v[52:55]
	v_mfma_f32_16x16x32_bf16 v[48:51], v[196:199], v[204:207], v[48:51]
	v_mfma_f32_16x16x32_bf16 v[36:39], v[188:191], v[212:215], v[36:39]
	v_mfma_f32_16x16x32_bf16 v[32:35], v[196:199], v[212:215], v[32:35]
	v_mfma_f32_16x16x32_bf16 v[20:23], v[188:191], v[220:223], v[20:23]
	v_mfma_f32_16x16x32_bf16 v[16:19], v[196:199], v[220:223], v[16:19]
	s_setprio 3
	s_barrier
	v_mfma_f32_16x16x32_bf16 v[4:7], v[188:191], v[228:231], v[4:7]
	v_mfma_f32_16x16x32_bf16 v[0:3], v[196:199], v[228:231], v[0:3]
	s_setprio 0
	s_add_i32 s57, 0, 0x18000
	s_add_i32 s58, 0, 0x1c000
	v_add_u32_e32 v156, s57, v163
	v_add_u32_e32 v177, s58, v163
	ds_read_b128 v[144:147], v156
	ds_read_b128 v[148:151], v156 offset:1024
	ds_read_b128 v[152:155], v156 offset:2048
	ds_read_b128 v[156:159], v156 offset:3072
	ds_read_b128 v[184:187], v177
	ds_read_b128 v[188:191], v177 offset:1024
	ds_read_b128 v[192:195], v177 offset:2048
	ds_read_b128 v[196:199], v177 offset:3072
	v_lshl_add_u64 v[232:233], s[34:35], 0, v[128:129]
	s_mov_b32 m0, s38
	v_lshl_add_u64 v[234:235], s[34:35], 0, v[132:133]
	global_load_lds_dwordx4 v[232:233], off
	s_mov_b32 m0, s39
	s_nop 0
	global_load_lds_dwordx4 v[234:235], off
	s_add_u32 s34, s34, 0x40000
	s_addc_u32 s35, s35, 0
	s_mov_b32 m0, s40
	v_lshl_add_u64 v[236:237], s[34:35], 0, v[128:129]
	ds_read_b128 v[200:203], v175 offset:32768
	ds_read_b128 v[204:207], v175 offset:33792
	ds_read_b128 v[208:211], v175 offset:34816
	ds_read_b128 v[212:215], v175 offset:35840
	ds_read_b128 v[216:219], v175 offset:36864
	ds_read_b128 v[220:223], v175 offset:37888
	ds_read_b128 v[224:227], v175 offset:38912
	ds_read_b128 v[228:231], v175 offset:39936
	global_load_lds_dwordx4 v[236:237], off
	v_lshl_add_u64 v[236:237], s[34:35], 0, v[132:133]
	s_mov_b32 m0, s41
	s_nop 0
	global_load_lds_dwordx4 v[236:237], off
	s_waitcnt vmcnt(8)
	s_waitcnt lgkmcnt(0)
	s_barrier
	s_waitcnt lgkmcnt(0)
	v_mfma_f32_16x16x32_bf16 v[124:127], v[144:147], v[200:203], v[124:127]
	v_mfma_f32_16x16x32_bf16 v[120:123], v[152:155], v[200:203], v[120:123]
	v_mfma_f32_16x16x32_bf16 v[108:111], v[144:147], v[208:211], v[108:111]
	v_mfma_f32_16x16x32_bf16 v[104:107], v[152:155], v[208:211], v[104:107]
	v_mfma_f32_16x16x32_bf16 v[92:95], v[144:147], v[216:219], v[92:95]
	v_mfma_f32_16x16x32_bf16 v[88:91], v[152:155], v[216:219], v[88:91]
	v_mfma_f32_16x16x32_bf16 v[76:79], v[144:147], v[224:227], v[76:79]
	v_mfma_f32_16x16x32_bf16 v[72:75], v[152:155], v[224:227], v[72:75]
	v_mfma_f32_16x16x32_bf16 v[124:127], v[148:151], v[204:207], v[124:127]
	v_mfma_f32_16x16x32_bf16 v[120:123], v[156:159], v[204:207], v[120:123]
	v_mfma_f32_16x16x32_bf16 v[108:111], v[148:151], v[212:215], v[108:111]
	v_mfma_f32_16x16x32_bf16 v[104:107], v[156:159], v[212:215], v[104:107]
	v_mfma_f32_16x16x32_bf16 v[92:95], v[148:151], v[220:223], v[92:95]
	v_mfma_f32_16x16x32_bf16 v[88:91], v[156:159], v[220:223], v[88:91]
	v_mfma_f32_16x16x32_bf16 v[76:79], v[148:151], v[228:231], v[76:79]
	v_mfma_f32_16x16x32_bf16 v[72:75], v[156:159], v[228:231], v[72:75]
	v_mfma_f32_16x16x32_bf16 v[116:119], v[184:187], v[200:203], v[116:119]
	v_mfma_f32_16x16x32_bf16 v[112:115], v[192:195], v[200:203], v[112:115]
	v_mfma_f32_16x16x32_bf16 v[100:103], v[184:187], v[208:211], v[100:103]
	v_mfma_f32_16x16x32_bf16 v[96:99], v[192:195], v[208:211], v[96:99]
	v_mfma_f32_16x16x32_bf16 v[84:87], v[184:187], v[216:219], v[84:87]
	v_mfma_f32_16x16x32_bf16 v[80:83], v[192:195], v[216:219], v[80:83]
	v_mfma_f32_16x16x32_bf16 v[68:71], v[184:187], v[224:227], v[68:71]
	v_mfma_f32_16x16x32_bf16 v[64:67], v[192:195], v[224:227], v[64:67]
	v_mfma_f32_16x16x32_bf16 v[116:119], v[188:191], v[204:207], v[116:119]
	v_mfma_f32_16x16x32_bf16 v[112:115], v[196:199], v[204:207], v[112:115]
	v_mfma_f32_16x16x32_bf16 v[100:103], v[188:191], v[212:215], v[100:103]
	v_mfma_f32_16x16x32_bf16 v[96:99], v[196:199], v[212:215], v[96:99]
	v_mfma_f32_16x16x32_bf16 v[84:87], v[188:191], v[220:223], v[84:87]
	v_mfma_f32_16x16x32_bf16 v[80:83], v[196:199], v[220:223], v[80:83]
	s_setprio 3
	s_barrier
	v_mfma_f32_16x16x32_bf16 v[68:71], v[188:191], v[228:231], v[68:71]
	v_mfma_f32_16x16x32_bf16 v[64:67], v[196:199], v[228:231], v[64:67]
	s_setprio 0
	s_add_i32 s34, s57, s37
	v_lshl_add_u64 v[160:161], v[160:161], 0, s[14:15]
	s_mov_b32 m0, s34
	ds_read_b128 v[200:203], v175 offset:49152
	ds_read_b128 v[204:207], v175 offset:50176
	ds_read_b128 v[208:211], v175 offset:51200
	ds_read_b128 v[212:215], v175 offset:52224
	ds_read_b128 v[216:219], v175 offset:53248
	ds_read_b128 v[220:223], v175 offset:54272
	ds_read_b128 v[224:227], v175 offset:55296
	ds_read_b128 v[228:231], v175 offset:56320
	global_load_lds_dwordx4 v[160:161], off
	s_add_i32 m0, s34, 0x2000
	s_add_u32 s30, s30, 0x40080
	v_lshl_add_u64 v[160:161], v[178:179], 0, s[14:15]
	s_addc_u32 s31, s31, 0
	s_add_i32 s34, s58, s37
	global_load_lds_dwordx4 v[160:161], off
	v_lshl_add_u64 v[160:161], s[30:31], 0, v[130:131]
	s_mov_b32 m0, s34
	s_nop 0
	global_load_lds_dwordx4 v[160:161], off
	v_lshl_add_u64 v[160:161], s[30:31], 0, v[134:135]
	s_add_i32 m0, s34, 0x2000
	s_nop 0
	global_load_lds_dwordx4 v[160:161], off
	s_waitcnt vmcnt(6)
	s_waitcnt lgkmcnt(0)
	s_barrier
	s_waitcnt lgkmcnt(0)
	v_mfma_f32_16x16x32_bf16 v[60:63], v[144:147], v[200:203], v[60:63]
	v_mfma_f32_16x16x32_bf16 v[56:59], v[152:155], v[200:203], v[56:59]
	v_mfma_f32_16x16x32_bf16 v[44:47], v[144:147], v[208:211], v[44:47]
	v_mfma_f32_16x16x32_bf16 v[40:43], v[152:155], v[208:211], v[40:43]
	v_mfma_f32_16x16x32_bf16 v[28:31], v[144:147], v[216:219], v[28:31]
	v_mfma_f32_16x16x32_bf16 v[24:27], v[152:155], v[216:219], v[24:27]
	v_mfma_f32_16x16x32_bf16 v[12:15], v[144:147], v[224:227], v[12:15]
	v_mfma_f32_16x16x32_bf16 v[8:11], v[152:155], v[224:227], v[8:11]
	v_mfma_f32_16x16x32_bf16 v[60:63], v[148:151], v[204:207], v[60:63]
	v_mfma_f32_16x16x32_bf16 v[56:59], v[156:159], v[204:207], v[56:59]
	v_mfma_f32_16x16x32_bf16 v[44:47], v[148:151], v[212:215], v[44:47]
	v_mfma_f32_16x16x32_bf16 v[40:43], v[156:159], v[212:215], v[40:43]
	v_mfma_f32_16x16x32_bf16 v[28:31], v[148:151], v[220:223], v[28:31]
	v_mfma_f32_16x16x32_bf16 v[24:27], v[156:159], v[220:223], v[24:27]
	v_mfma_f32_16x16x32_bf16 v[12:15], v[148:151], v[228:231], v[12:15]
	v_mfma_f32_16x16x32_bf16 v[8:11], v[156:159], v[228:231], v[8:11]
	v_mfma_f32_16x16x32_bf16 v[52:55], v[184:187], v[200:203], v[52:55]
	v_mfma_f32_16x16x32_bf16 v[48:51], v[192:195], v[200:203], v[48:51]
	v_mfma_f32_16x16x32_bf16 v[36:39], v[184:187], v[208:211], v[36:39]
	v_mfma_f32_16x16x32_bf16 v[32:35], v[192:195], v[208:211], v[32:35]
	v_mfma_f32_16x16x32_bf16 v[20:23], v[184:187], v[216:219], v[20:23]
	v_mfma_f32_16x16x32_bf16 v[16:19], v[192:195], v[216:219], v[16:19]
	v_mfma_f32_16x16x32_bf16 v[4:7], v[184:187], v[224:227], v[4:7]
	v_mfma_f32_16x16x32_bf16 v[0:3], v[192:195], v[224:227], v[0:3]
	v_mfma_f32_16x16x32_bf16 v[52:55], v[188:191], v[204:207], v[52:55]
	v_mfma_f32_16x16x32_bf16 v[48:51], v[196:199], v[204:207], v[48:51]
	v_mfma_f32_16x16x32_bf16 v[36:39], v[188:191], v[212:215], v[36:39]
	v_mfma_f32_16x16x32_bf16 v[32:35], v[196:199], v[212:215], v[32:35]
	v_mfma_f32_16x16x32_bf16 v[20:23], v[188:191], v[220:223], v[20:23]
	v_mfma_f32_16x16x32_bf16 v[16:19], v[196:199], v[220:223], v[16:19]
	s_setprio 3
	s_barrier
	v_mfma_f32_16x16x32_bf16 v[4:7], v[188:191], v[228:231], v[4:7]
	v_mfma_f32_16x16x32_bf16 v[0:3], v[196:199], v[228:231], v[0:3]
	s_setprio 0
	v_lshl_add_u64 v[160:161], v[232:233], 0, s[14:15]
	s_mov_b32 m0, s42
	s_nop 0
	global_load_lds_dwordx4 v[160:161], off
	v_lshl_add_u64 v[160:161], v[234:235], 0, s[14:15]
	s_mov_b32 m0, s43
	s_nop 0
	global_load_lds_dwordx4 v[160:161], off
	s_add_i32 s56, s56, 2
	s_add_u32 s28, s28, 0x100
	s_addc_u32 s29, s29, 0
	s_add_u32 s54, s54, 0x100
	s_addc_u32 s55, s55, 0
	s_cmp_gt_u32 s56, 13

.LBB0_1290:
	s_ashr_i32 s17, s16, 31
	s_lshl_b64 s[18:19], s[16:17], 19
	s_add_u32 s18, s48, s18
	s_addc_u32 s19, s49, s19
	s_add_u32 s98, s24, 0x700
	s_addc_u32 s99, s25, 0
	s_and_b64 s[20:21], s[4:5], exec
	s_cselect_b32 s17, s19, s99
	s_cselect_b32 s23, s18, s98
	s_ashr_i32 s15, s14, 31
	s_lshl_b64 s[20:21], s[14:15], 19
	s_add_u32 s20, s30, s20
	s_addc_u32 s21, s31, s21
	s_add_u32 s98, s26, 0x700
	s_addc_u32 s99, s27, 0
	s_and_b64 s[28:29], s[4:5], exec
	s_cselect_b32 s15, s21, s99
	s_cselect_b32 s44, s20, s98
	s_add_u32 s24, s24, 0x40080
	s_addc_u32 s25, s25, 0
	s_add_u32 s45, s26, 0x100
	s_addc_u32 s46, s27, 0
	s_mov_b32 s47, -2
	s_waitcnt lgkmcnt(0)
	ds_read_b128 v[144:147], v151
	ds_read_b128 v[156:159], v151 offset:1024
	ds_read_b128 v[160:163], v151 offset:2048
	ds_read_b128 v[164:167], v151 offset:3072
	ds_read_b128 v[168:171], v152
	ds_read_b128 v[172:175], v152 offset:1024
	ds_read_b128 v[176:179], v152 offset:2048
	ds_read_b128 v[184:187], v152 offset:3072
	s_add_u32 s26, s24, 0xfffc0080
	s_addc_u32 s27, s25, -1
	s_cmp_eq_u32 s47, 12
	s_cselect_b32 s29, s17, s27
	s_cselect_b32 s28, s23, s26
	s_cselect_b32 s27, s15, s46
	s_cselect_b32 s26, s44, s45
	v_lshl_add_u64 v[220:221], s[24:25], 0, v[136:137]
	s_add_i32 m0, s34, 0xc000
	ds_read_b128 v[188:191], v153
	ds_read_b128 v[192:195], v153 offset:1024
	ds_read_b128 v[196:199], v153 offset:2048
	ds_read_b128 v[200:203], v153 offset:3072
	ds_read_b128 v[204:207], v153 offset:4096
	ds_read_b128 v[208:211], v153 offset:5120
	ds_read_b128 v[212:215], v153 offset:6144
	ds_read_b128 v[216:219], v153 offset:7168
	global_load_lds_dwordx4 v[220:221], off
	v_lshl_add_u64 v[220:221], s[24:25], 0, v[138:139]
	s_add_i32 m0, s34, 0xe000
	s_nop 0
	global_load_lds_dwordx4 v[220:221], off
	s_waitcnt vmcnt(8)
	s_waitcnt lgkmcnt(0)
	s_barrier
	s_waitcnt lgkmcnt(0)
	v_mfma_f32_16x16x32_bf16 v[124:127], v[144:147], v[188:191], 0
	v_mfma_f32_16x16x32_bf16 v[120:123], v[160:163], v[188:191], 0
	v_mfma_f32_16x16x32_bf16 v[108:111], v[144:147], v[196:199], 0
	v_mfma_f32_16x16x32_bf16 v[104:107], v[160:163], v[196:199], 0
	v_mfma_f32_16x16x32_bf16 v[92:95], v[144:147], v[204:207], 0
	v_mfma_f32_16x16x32_bf16 v[88:91], v[160:163], v[204:207], 0
	v_mfma_f32_16x16x32_bf16 v[76:79], v[144:147], v[212:215], 0
	v_mfma_f32_16x16x32_bf16 v[72:75], v[160:163], v[212:215], 0
	v_mfma_f32_16x16x32_bf16 v[124:127], v[156:159], v[192:195], v[124:127]
	v_mfma_f32_16x16x32_bf16 v[120:123], v[164:167], v[192:195], v[120:123]
	v_mfma_f32_16x16x32_bf16 v[108:111], v[156:159], v[200:203], v[108:111]
	v_mfma_f32_16x16x32_bf16 v[104:107], v[164:167], v[200:203], v[104:107]
	v_mfma_f32_16x16x32_bf16 v[92:95], v[156:159], v[208:211], v[92:95]
	v_mfma_f32_16x16x32_bf16 v[88:91], v[164:167], v[208:211], v[88:91]
	v_mfma_f32_16x16x32_bf16 v[76:79], v[156:159], v[216:219], v[76:79]
	v_mfma_f32_16x16x32_bf16 v[72:75], v[164:167], v[216:219], v[72:75]
	v_mfma_f32_16x16x32_bf16 v[116:119], v[168:171], v[188:191], 0
	v_mfma_f32_16x16x32_bf16 v[112:115], v[176:179], v[188:191], 0
	v_mfma_f32_16x16x32_bf16 v[100:103], v[168:171], v[196:199], 0
	v_mfma_f32_16x16x32_bf16 v[96:99], v[176:179], v[196:199], 0
	v_mfma_f32_16x16x32_bf16 v[84:87], v[168:171], v[204:207], 0
	v_mfma_f32_16x16x32_bf16 v[80:83], v[176:179], v[204:207], 0
	v_mfma_f32_16x16x32_bf16 v[68:71], v[168:171], v[212:215], 0
	v_mfma_f32_16x16x32_bf16 v[64:67], v[176:179], v[212:215], 0
	v_mfma_f32_16x16x32_bf16 v[116:119], v[172:175], v[192:195], v[116:119]
	v_mfma_f32_16x16x32_bf16 v[112:115], v[184:187], v[192:195], v[112:115]
	v_mfma_f32_16x16x32_bf16 v[100:103], v[172:175], v[200:203], v[100:103]
	v_mfma_f32_16x16x32_bf16 v[96:99], v[184:187], v[200:203], v[96:99]
	v_mfma_f32_16x16x32_bf16 v[84:87], v[172:175], v[208:211], v[84:87]
	v_mfma_f32_16x16x32_bf16 v[80:83], v[184:187], v[208:211], v[80:83]
	s_setprio 3
	s_barrier
	v_mfma_f32_16x16x32_bf16 v[68:71], v[172:175], v[216:219], v[68:71]
	v_mfma_f32_16x16x32_bf16 v[64:67], v[184:187], v[216:219], v[64:67]
	s_setprio 0
	s_add_i32 s50, s41, s33
	v_lshl_add_u64 v[220:221], s[26:27], 0, v[130:131]
	s_mov_b32 m0, s50
	ds_read_b128 v[188:191], v153 offset:16384
	ds_read_b128 v[192:195], v153 offset:17408
	ds_read_b128 v[196:199], v153 offset:18432
	ds_read_b128 v[200:203], v153 offset:19456
	ds_read_b128 v[204:207], v153 offset:20480
	ds_read_b128 v[208:211], v153 offset:21504
	ds_read_b128 v[212:215], v153 offset:22528
	ds_read_b128 v[216:219], v153 offset:23552
	global_load_lds_dwordx4 v[220:221], off
	s_add_i32 m0, s50, 0x2000
	s_add_u32 s50, s26, 0x40000
	v_lshl_add_u64 v[222:223], s[26:27], 0, v[134:135]
	s_addc_u32 s51, s27, 0
	s_add_i32 s52, s42, s33
	global_load_lds_dwordx4 v[222:223], off
	v_lshl_add_u64 v[224:225], s[50:51], 0, v[130:131]
	s_mov_b32 m0, s52
	global_load_lds_dwordx4 v[224:225], off
	v_lshl_add_u64 v[224:225], s[50:51], 0, v[134:135]
	s_add_i32 m0, s52, 0x2000
	s_nop 0
	global_load_lds_dwordx4 v[224:225], off
	s_waitcnt vmcnt(6)
	s_waitcnt lgkmcnt(0)
	s_barrier
	s_waitcnt lgkmcnt(0)
	v_mfma_f32_16x16x32_bf16 v[60:63], v[144:147], v[188:191], 0
	v_mfma_f32_16x16x32_bf16 v[56:59], v[160:163], v[188:191], 0
	v_mfma_f32_16x16x32_bf16 v[44:47], v[144:147], v[196:199], 0
	v_mfma_f32_16x16x32_bf16 v[40:43], v[160:163], v[196:199], 0
	v_mfma_f32_16x16x32_bf16 v[28:31], v[144:147], v[204:207], 0
	v_mfma_f32_16x16x32_bf16 v[24:27], v[160:163], v[204:207], 0
	v_mfma_f32_16x16x32_bf16 v[12:15], v[144:147], v[212:215], 0
	v_mfma_f32_16x16x32_bf16 v[8:11], v[160:163], v[212:215], 0
	v_mfma_f32_16x16x32_bf16 v[60:63], v[156:159], v[192:195], v[60:63]
	v_mfma_f32_16x16x32_bf16 v[56:59], v[164:167], v[192:195], v[56:59]
	v_mfma_f32_16x16x32_bf16 v[44:47], v[156:159], v[200:203], v[44:47]
	v_mfma_f32_16x16x32_bf16 v[40:43], v[164:167], v[200:203], v[40:43]
	v_mfma_f32_16x16x32_bf16 v[28:31], v[156:159], v[208:211], v[28:31]
	v_mfma_f32_16x16x32_bf16 v[24:27], v[164:167], v[208:211], v[24:27]
	v_mfma_f32_16x16x32_bf16 v[12:15], v[156:159], v[216:219], v[12:15]
	v_mfma_f32_16x16x32_bf16 v[8:11], v[164:167], v[216:219], v[8:11]
	v_mfma_f32_16x16x32_bf16 v[52:55], v[168:171], v[188:191], 0
	v_mfma_f32_16x16x32_bf16 v[48:51], v[176:179], v[188:191], 0
	v_mfma_f32_16x16x32_bf16 v[36:39], v[168:171], v[196:199], 0
	v_mfma_f32_16x16x32_bf16 v[32:35], v[176:179], v[196:199], 0
	v_mfma_f32_16x16x32_bf16 v[20:23], v[168:171], v[204:207], 0
	v_mfma_f32_16x16x32_bf16 v[16:19], v[176:179], v[204:207], 0
	v_mfma_f32_16x16x32_bf16 v[4:7], v[168:171], v[212:215], 0
	v_mfma_f32_16x16x32_bf16 v[0:3], v[176:179], v[212:215], 0
	v_mfma_f32_16x16x32_bf16 v[52:55], v[172:175], v[192:195], v[52:55]
	v_mfma_f32_16x16x32_bf16 v[48:51], v[184:187], v[192:195], v[48:51]
	v_mfma_f32_16x16x32_bf16 v[36:39], v[172:175], v[200:203], v[36:39]
	v_mfma_f32_16x16x32_bf16 v[32:35], v[184:187], v[200:203], v[32:35]
	v_mfma_f32_16x16x32_bf16 v[20:23], v[172:175], v[208:211], v[20:23]
	v_mfma_f32_16x16x32_bf16 v[16:19], v[184:187], v[208:211], v[16:19]
	s_setprio 3
	s_barrier
	v_mfma_f32_16x16x32_bf16 v[4:7], v[172:175], v[216:219], v[4:7]
	v_mfma_f32_16x16x32_bf16 v[0:3], v[184:187], v[216:219], v[0:3]
	s_setprio 0
	s_add_i32 s50, 0, 0x18000
	v_add_u32_e32 v155, s50, v149
	s_add_i32 s51, 0, 0x1c000
	ds_read_b128 v[144:147], v155
	ds_read_b128 v[156:159], v155 offset:1024
	ds_read_b128 v[160:163], v155 offset:2048
	ds_read_b128 v[164:167], v155 offset:3072
	v_add_u32_e32 v155, s51, v149
	ds_read_b128 v[168:171], v155
	ds_read_b128 v[172:175], v155 offset:1024
	ds_read_b128 v[176:179], v155 offset:2048
	ds_read_b128 v[184:187], v155 offset:3072
	v_lshl_add_u64 v[224:225], s[28:29], 0, v[128:129]
	s_mov_b32 m0, s34
	v_lshl_add_u64 v[226:227], s[28:29], 0, v[132:133]
	global_load_lds_dwordx4 v[224:225], off
	s_mov_b32 m0, s35
	s_nop 0
	global_load_lds_dwordx4 v[226:227], off
	s_add_u32 s28, s28, 0x40000
	s_addc_u32 s29, s29, 0
	s_mov_b32 m0, s36
	v_lshl_add_u64 v[228:229], s[28:29], 0, v[128:129]
	ds_read_b128 v[188:191], v153 offset:32768
	ds_read_b128 v[192:195], v153 offset:33792
	ds_read_b128 v[196:199], v153 offset:34816
	ds_read_b128 v[200:203], v153 offset:35840
	ds_read_b128 v[204:207], v153 offset:36864
	ds_read_b128 v[208:211], v153 offset:37888
	ds_read_b128 v[212:215], v153 offset:38912
	ds_read_b128 v[216:219], v153 offset:39936
	global_load_lds_dwordx4 v[228:229], off
	v_lshl_add_u64 v[228:229], s[28:29], 0, v[132:133]
	s_mov_b32 m0, s37
	s_nop 0
	global_load_lds_dwordx4 v[228:229], off
	s_waitcnt vmcnt(8)
	s_waitcnt lgkmcnt(0)
	s_barrier
	s_waitcnt lgkmcnt(0)
	v_mfma_f32_16x16x32_bf16 v[124:127], v[144:147], v[188:191], v[124:127]
	v_mfma_f32_16x16x32_bf16 v[120:123], v[160:163], v[188:191], v[120:123]
	v_mfma_f32_16x16x32_bf16 v[108:111], v[144:147], v[196:199], v[108:111]
	v_mfma_f32_16x16x32_bf16 v[104:107], v[160:163], v[196:199], v[104:107]
	v_mfma_f32_16x16x32_bf16 v[92:95], v[144:147], v[204:207], v[92:95]
	v_mfma_f32_16x16x32_bf16 v[88:91], v[160:163], v[204:207], v[88:91]
	v_mfma_f32_16x16x32_bf16 v[76:79], v[144:147], v[212:215], v[76:79]
	v_mfma_f32_16x16x32_bf16 v[72:75], v[160:163], v[212:215], v[72:75]
	v_mfma_f32_16x16x32_bf16 v[124:127], v[156:159], v[192:195], v[124:127]
	v_mfma_f32_16x16x32_bf16 v[120:123], v[164:167], v[192:195], v[120:123]
	v_mfma_f32_16x16x32_bf16 v[108:111], v[156:159], v[200:203], v[108:111]
	v_mfma_f32_16x16x32_bf16 v[104:107], v[164:167], v[200:203], v[104:107]
	v_mfma_f32_16x16x32_bf16 v[92:95], v[156:159], v[208:211], v[92:95]
	v_mfma_f32_16x16x32_bf16 v[88:91], v[164:167], v[208:211], v[88:91]
	v_mfma_f32_16x16x32_bf16 v[76:79], v[156:159], v[216:219], v[76:79]
	v_mfma_f32_16x16x32_bf16 v[72:75], v[164:167], v[216:219], v[72:75]
	v_mfma_f32_16x16x32_bf16 v[116:119], v[168:171], v[188:191], v[116:119]
	v_mfma_f32_16x16x32_bf16 v[112:115], v[176:179], v[188:191], v[112:115]
	v_mfma_f32_16x16x32_bf16 v[100:103], v[168:171], v[196:199], v[100:103]
	v_mfma_f32_16x16x32_bf16 v[96:99], v[176:179], v[196:199], v[96:99]
	v_mfma_f32_16x16x32_bf16 v[84:87], v[168:171], v[204:207], v[84:87]
	v_mfma_f32_16x16x32_bf16 v[80:83], v[176:179], v[204:207], v[80:83]
	v_mfma_f32_16x16x32_bf16 v[68:71], v[168:171], v[212:215], v[68:71]
	v_mfma_f32_16x16x32_bf16 v[64:67], v[176:179], v[212:215], v[64:67]
	v_mfma_f32_16x16x32_bf16 v[116:119], v[172:175], v[192:195], v[116:119]
	v_mfma_f32_16x16x32_bf16 v[112:115], v[184:187], v[192:195], v[112:115]
	v_mfma_f32_16x16x32_bf16 v[100:103], v[172:175], v[200:203], v[100:103]
	v_mfma_f32_16x16x32_bf16 v[96:99], v[184:187], v[200:203], v[96:99]
	v_mfma_f32_16x16x32_bf16 v[84:87], v[172:175], v[208:211], v[84:87]
	v_mfma_f32_16x16x32_bf16 v[80:83], v[184:187], v[208:211], v[80:83]
	s_setprio 3
	s_barrier
	v_mfma_f32_16x16x32_bf16 v[68:71], v[172:175], v[216:219], v[68:71]
	v_mfma_f32_16x16x32_bf16 v[64:67], v[184:187], v[216:219], v[64:67]
	s_setprio 0
	s_add_i32 s28, s50, s33
	v_lshl_add_u64 v[220:221], v[220:221], 0, s[10:11]
	s_mov_b32 m0, s28
	ds_read_b128 v[188:191], v153 offset:49152
	ds_read_b128 v[192:195], v153 offset:50176
	ds_read_b128 v[196:199], v153 offset:51200
	ds_read_b128 v[200:203], v153 offset:52224
	ds_read_b128 v[204:207], v153 offset:53248
	ds_read_b128 v[208:211], v153 offset:54272
	ds_read_b128 v[212:215], v153 offset:55296
	ds_read_b128 v[216:219], v153 offset:56320
	global_load_lds_dwordx4 v[220:221], off
	s_add_i32 m0, s28, 0x2000
	s_add_u32 s26, s26, 0x40080
	v_lshl_add_u64 v[220:221], v[222:223], 0, s[10:11]
	s_addc_u32 s27, s27, 0
	s_add_i32 s28, s51, s33
	global_load_lds_dwordx4 v[220:221], off
	v_lshl_add_u64 v[220:221], s[26:27], 0, v[130:131]
	s_mov_b32 m0, s28
	s_nop 0
	global_load_lds_dwordx4 v[220:221], off
	v_lshl_add_u64 v[220:221], s[26:27], 0, v[134:135]
	s_add_i32 m0, s28, 0x2000
	s_nop 0
	global_load_lds_dwordx4 v[220:221], off
	s_waitcnt vmcnt(6)
	s_waitcnt lgkmcnt(0)
	s_barrier
	s_waitcnt lgkmcnt(0)
	v_mfma_f32_16x16x32_bf16 v[60:63], v[144:147], v[188:191], v[60:63]
	v_mfma_f32_16x16x32_bf16 v[56:59], v[160:163], v[188:191], v[56:59]
	v_mfma_f32_16x16x32_bf16 v[44:47], v[144:147], v[196:199], v[44:47]
	v_mfma_f32_16x16x32_bf16 v[40:43], v[160:163], v[196:199], v[40:43]
	v_mfma_f32_16x16x32_bf16 v[28:31], v[144:147], v[204:207], v[28:31]
	v_mfma_f32_16x16x32_bf16 v[24:27], v[160:163], v[204:207], v[24:27]
	v_mfma_f32_16x16x32_bf16 v[12:15], v[144:147], v[212:215], v[12:15]
	v_mfma_f32_16x16x32_bf16 v[8:11], v[160:163], v[212:215], v[8:11]
	v_mfma_f32_16x16x32_bf16 v[60:63], v[156:159], v[192:195], v[60:63]
	v_mfma_f32_16x16x32_bf16 v[56:59], v[164:167], v[192:195], v[56:59]
	v_mfma_f32_16x16x32_bf16 v[44:47], v[156:159], v[200:203], v[44:47]
	v_mfma_f32_16x16x32_bf16 v[40:43], v[164:167], v[200:203], v[40:43]
	v_mfma_f32_16x16x32_bf16 v[28:31], v[156:159], v[208:211], v[28:31]
	v_mfma_f32_16x16x32_bf16 v[24:27], v[164:167], v[208:211], v[24:27]
	v_mfma_f32_16x16x32_bf16 v[12:15], v[156:159], v[216:219], v[12:15]
	v_mfma_f32_16x16x32_bf16 v[8:11], v[164:167], v[216:219], v[8:11]
	v_mfma_f32_16x16x32_bf16 v[52:55], v[168:171], v[188:191], v[52:55]
	v_mfma_f32_16x16x32_bf16 v[48:51], v[176:179], v[188:191], v[48:51]
	v_mfma_f32_16x16x32_bf16 v[36:39], v[168:171], v[196:199], v[36:39]
	v_mfma_f32_16x16x32_bf16 v[32:35], v[176:179], v[196:199], v[32:35]
	v_mfma_f32_16x16x32_bf16 v[20:23], v[168:171], v[204:207], v[20:23]
	v_mfma_f32_16x16x32_bf16 v[16:19], v[176:179], v[204:207], v[16:19]
	v_mfma_f32_16x16x32_bf16 v[4:7], v[168:171], v[212:215], v[4:7]
	v_mfma_f32_16x16x32_bf16 v[0:3], v[176:179], v[212:215], v[0:3]
	v_mfma_f32_16x16x32_bf16 v[52:55], v[172:175], v[192:195], v[52:55]
	v_mfma_f32_16x16x32_bf16 v[48:51], v[184:187], v[192:195], v[48:51]
	v_mfma_f32_16x16x32_bf16 v[36:39], v[172:175], v[200:203], v[36:39]
	v_mfma_f32_16x16x32_bf16 v[32:35], v[184:187], v[200:203], v[32:35]
	v_mfma_f32_16x16x32_bf16 v[20:23], v[172:175], v[208:211], v[20:23]
	v_mfma_f32_16x16x32_bf16 v[16:19], v[184:187], v[208:211], v[16:19]
	s_setprio 3
	s_barrier
	v_mfma_f32_16x16x32_bf16 v[4:7], v[172:175], v[216:219], v[4:7]
	v_mfma_f32_16x16x32_bf16 v[0:3], v[184:187], v[216:219], v[0:3]
	s_setprio 0
	v_lshl_add_u64 v[220:221], v[224:225], 0, s[10:11]
	s_mov_b32 m0, s39
	s_nop 0
	global_load_lds_dwordx4 v[220:221], off
	v_lshl_add_u64 v[220:221], v[226:227], 0, s[10:11]
	s_mov_b32 m0, s40
	s_nop 0
	global_load_lds_dwordx4 v[220:221], off
	s_add_i32 s47, s47, 2
	s_add_u32 s24, s24, 0x100
	s_addc_u32 s25, s25, 0
	s_add_u32 s45, s45, 0x100
	s_addc_u32 s46, s46, 0
	s_cmp_gt_u32 s47, 13

.LBB0_1378:
	s_ashr_i32 s13, s12, 31
	s_lshl_b64 s[14:15], s[12:13], 19
	s_add_u32 s14, s74, s14
	s_addc_u32 s15, s75, s15
	s_add_u32 s98, s20, 0x700
	s_addc_u32 s99, s21, 0
	s_and_b64 s[16:17], s[0:1], exec
	s_cselect_b32 s13, s15, s99
	s_cselect_b32 s42, s14, s98
	s_ashr_i32 s11, s10, 31
	s_lshl_b64 s[16:17], s[10:11], 19
	s_add_u32 s16, s26, s16
	s_addc_u32 s17, s27, s17
	s_add_u32 s98, s22, 0x700
	s_addc_u32 s99, s23, 0
	s_and_b64 s[24:25], s[0:1], exec
	s_cselect_b32 s11, s17, s99
	s_cselect_b32 s43, s16, s98
	s_add_u32 s20, s20, 0x40080
	s_addc_u32 s21, s21, 0
	s_add_u32 s44, s22, 0x100
	s_addc_u32 s45, s23, 0
	s_mov_b32 s46, -2
	ds_read_b128 v[154:157], v151
	ds_read_b128 v[158:161], v151 offset:1024
	ds_read_b128 v[162:165], v151 offset:2048
	ds_read_b128 v[166:169], v151 offset:3072
	ds_read_b128 v[170:173], v152
	ds_read_b128 v[174:177], v152 offset:1024
	ds_read_b128 v[184:187], v152 offset:2048
	ds_read_b128 v[188:191], v152 offset:3072
	s_add_u32 s22, s20, 0xfffc0080
	s_addc_u32 s23, s21, -1
	s_cmp_eq_u32 s46, 12
	s_cselect_b32 s25, s13, s23
	s_cselect_b32 s24, s42, s22
	s_cselect_b32 s23, s11, s45
	s_cselect_b32 s22, s43, s44
	v_lshl_add_u64 v[178:179], s[20:21], 0, v[136:137]
	s_add_i32 m0, s19, 0xc000
	ds_read_b128 v[192:195], v153
	ds_read_b128 v[196:199], v153 offset:1024
	ds_read_b128 v[200:203], v153 offset:2048
	ds_read_b128 v[204:207], v153 offset:3072
	ds_read_b128 v[208:211], v153 offset:4096
	ds_read_b128 v[212:215], v153 offset:5120
	ds_read_b128 v[216:219], v153 offset:6144
	ds_read_b128 v[220:223], v153 offset:7168
	global_load_lds_dwordx4 v[178:179], off
	v_lshl_add_u64 v[178:179], s[20:21], 0, v[138:139]
	s_add_i32 m0, s19, 0xe000
	s_nop 0
	global_load_lds_dwordx4 v[178:179], off
	s_waitcnt vmcnt(8)
	s_waitcnt lgkmcnt(0)
	s_barrier
	s_waitcnt lgkmcnt(0)
	v_mfma_f32_16x16x32_bf16 v[124:127], v[154:157], v[192:195], 0
	v_mfma_f32_16x16x32_bf16 v[116:119], v[162:165], v[192:195], 0
	v_mfma_f32_16x16x32_bf16 v[108:111], v[154:157], v[200:203], 0
	v_mfma_f32_16x16x32_bf16 v[100:103], v[162:165], v[200:203], 0
	v_mfma_f32_16x16x32_bf16 v[92:95], v[154:157], v[208:211], 0
	v_mfma_f32_16x16x32_bf16 v[84:87], v[162:165], v[208:211], 0
	v_mfma_f32_16x16x32_bf16 v[76:79], v[154:157], v[216:219], 0
	v_mfma_f32_16x16x32_bf16 v[68:71], v[162:165], v[216:219], 0
	v_mfma_f32_16x16x32_bf16 v[124:127], v[158:161], v[196:199], v[124:127]
	v_mfma_f32_16x16x32_bf16 v[116:119], v[166:169], v[196:199], v[116:119]
	v_mfma_f32_16x16x32_bf16 v[108:111], v[158:161], v[204:207], v[108:111]
	v_mfma_f32_16x16x32_bf16 v[100:103], v[166:169], v[204:207], v[100:103]
	v_mfma_f32_16x16x32_bf16 v[92:95], v[158:161], v[212:215], v[92:95]
	v_mfma_f32_16x16x32_bf16 v[84:87], v[166:169], v[212:215], v[84:87]
	v_mfma_f32_16x16x32_bf16 v[76:79], v[158:161], v[220:223], v[76:79]
	v_mfma_f32_16x16x32_bf16 v[68:71], v[166:169], v[220:223], v[68:71]
	v_mfma_f32_16x16x32_bf16 v[120:123], v[170:173], v[192:195], 0
	v_mfma_f32_16x16x32_bf16 v[112:115], v[184:187], v[192:195], 0
	v_mfma_f32_16x16x32_bf16 v[104:107], v[170:173], v[200:203], 0
	v_mfma_f32_16x16x32_bf16 v[96:99], v[184:187], v[200:203], 0
	v_mfma_f32_16x16x32_bf16 v[88:91], v[170:173], v[208:211], 0
	v_mfma_f32_16x16x32_bf16 v[80:83], v[184:187], v[208:211], 0
	v_mfma_f32_16x16x32_bf16 v[72:75], v[170:173], v[216:219], 0
	v_mfma_f32_16x16x32_bf16 v[64:67], v[184:187], v[216:219], 0
	v_mfma_f32_16x16x32_bf16 v[120:123], v[174:177], v[196:199], v[120:123]
	v_mfma_f32_16x16x32_bf16 v[112:115], v[188:191], v[196:199], v[112:115]
	v_mfma_f32_16x16x32_bf16 v[104:107], v[174:177], v[204:207], v[104:107]
	v_mfma_f32_16x16x32_bf16 v[96:99], v[188:191], v[204:207], v[96:99]
	v_mfma_f32_16x16x32_bf16 v[88:91], v[174:177], v[212:215], v[88:91]
	v_mfma_f32_16x16x32_bf16 v[80:83], v[188:191], v[212:215], v[80:83]
	s_setprio 3
	s_barrier
	v_mfma_f32_16x16x32_bf16 v[72:75], v[174:177], v[220:223], v[72:75]
	v_mfma_f32_16x16x32_bf16 v[64:67], v[188:191], v[220:223], v[64:67]
	s_setprio 0
	s_add_i32 s47, s36, s28
	v_lshl_add_u64 v[178:179], s[22:23], 0, v[132:133]
	s_mov_b32 m0, s47
	ds_read_b128 v[192:195], v153 offset:16384
	ds_read_b128 v[196:199], v153 offset:17408
	ds_read_b128 v[200:203], v153 offset:18432
	ds_read_b128 v[204:207], v153 offset:19456
	ds_read_b128 v[208:211], v153 offset:20480
	ds_read_b128 v[212:215], v153 offset:21504
	ds_read_b128 v[216:219], v153 offset:22528
	ds_read_b128 v[220:223], v153 offset:23552
	global_load_lds_dwordx4 v[178:179], off
	s_add_i32 m0, s47, 0x2000
	s_add_u32 s48, s22, 0x40000
	v_lshl_add_u64 v[224:225], s[22:23], 0, v[128:129]
	s_addc_u32 s49, s23, 0
	s_add_i32 s47, s37, s28
	global_load_lds_dwordx4 v[224:225], off
	v_lshl_add_u64 v[226:227], s[48:49], 0, v[132:133]
	s_mov_b32 m0, s47
	global_load_lds_dwordx4 v[226:227], off
	v_lshl_add_u64 v[226:227], s[48:49], 0, v[128:129]
	s_add_i32 m0, s47, 0x2000
	s_nop 0
	global_load_lds_dwordx4 v[226:227], off
	s_waitcnt vmcnt(6)
	s_waitcnt lgkmcnt(0)
	s_barrier
	s_waitcnt lgkmcnt(0)
	v_mfma_f32_16x16x32_bf16 v[60:63], v[154:157], v[192:195], 0
	v_mfma_f32_16x16x32_bf16 v[52:55], v[162:165], v[192:195], 0
	v_mfma_f32_16x16x32_bf16 v[44:47], v[154:157], v[200:203], 0
	v_mfma_f32_16x16x32_bf16 v[36:39], v[162:165], v[200:203], 0
	v_mfma_f32_16x16x32_bf16 v[28:31], v[154:157], v[208:211], 0
	v_mfma_f32_16x16x32_bf16 v[20:23], v[162:165], v[208:211], 0
	v_mfma_f32_16x16x32_bf16 v[12:15], v[154:157], v[216:219], 0
	v_mfma_f32_16x16x32_bf16 v[4:7], v[162:165], v[216:219], 0
	v_mfma_f32_16x16x32_bf16 v[60:63], v[158:161], v[196:199], v[60:63]
	v_mfma_f32_16x16x32_bf16 v[52:55], v[166:169], v[196:199], v[52:55]
	v_mfma_f32_16x16x32_bf16 v[44:47], v[158:161], v[204:207], v[44:47]
	v_mfma_f32_16x16x32_bf16 v[36:39], v[166:169], v[204:207], v[36:39]
	v_mfma_f32_16x16x32_bf16 v[28:31], v[158:161], v[212:215], v[28:31]
	v_mfma_f32_16x16x32_bf16 v[20:23], v[166:169], v[212:215], v[20:23]
	v_mfma_f32_16x16x32_bf16 v[12:15], v[158:161], v[220:223], v[12:15]
	v_mfma_f32_16x16x32_bf16 v[4:7], v[166:169], v[220:223], v[4:7]
	v_mfma_f32_16x16x32_bf16 v[56:59], v[170:173], v[192:195], 0
	v_mfma_f32_16x16x32_bf16 v[48:51], v[184:187], v[192:195], 0
	v_mfma_f32_16x16x32_bf16 v[40:43], v[170:173], v[200:203], 0
	v_mfma_f32_16x16x32_bf16 v[32:35], v[184:187], v[200:203], 0
	v_mfma_f32_16x16x32_bf16 v[24:27], v[170:173], v[208:211], 0
	v_mfma_f32_16x16x32_bf16 v[16:19], v[184:187], v[208:211], 0
	v_mfma_f32_16x16x32_bf16 v[8:11], v[170:173], v[216:219], 0
	v_mfma_f32_16x16x32_bf16 v[0:3], v[184:187], v[216:219], 0
	v_mfma_f32_16x16x32_bf16 v[56:59], v[174:177], v[196:199], v[56:59]
	v_mfma_f32_16x16x32_bf16 v[48:51], v[188:191], v[196:199], v[48:51]
	v_mfma_f32_16x16x32_bf16 v[40:43], v[174:177], v[204:207], v[40:43]
	v_mfma_f32_16x16x32_bf16 v[32:35], v[188:191], v[204:207], v[32:35]
	v_mfma_f32_16x16x32_bf16 v[24:27], v[174:177], v[212:215], v[24:27]
	v_mfma_f32_16x16x32_bf16 v[16:19], v[188:191], v[212:215], v[16:19]
	s_setprio 3
	s_barrier
	v_mfma_f32_16x16x32_bf16 v[8:11], v[174:177], v[220:223], v[8:11]
	v_mfma_f32_16x16x32_bf16 v[0:3], v[188:191], v[220:223], v[0:3]
	s_setprio 0
	s_add_i32 s47, 0, 0x18000
	s_add_i32 s48, 0, 0x1c000
	v_add_u32_e32 v166, s47, v145
	v_add_u32_e32 v180, s48, v145
	ds_read_b128 v[154:157], v166
	ds_read_b128 v[158:161], v166 offset:1024
	ds_read_b128 v[162:165], v166 offset:2048
	ds_read_b128 v[166:169], v166 offset:3072
	ds_read_b128 v[170:173], v180
	ds_read_b128 v[174:177], v180 offset:1024
	ds_read_b128 v[184:187], v180 offset:2048
	ds_read_b128 v[188:191], v180 offset:3072
	v_lshl_add_u64 v[226:227], s[24:25], 0, v[134:135]
	s_mov_b32 m0, s19
	v_lshl_add_u64 v[228:229], s[24:25], 0, v[130:131]
	global_load_lds_dwordx4 v[226:227], off
	s_mov_b32 m0, s30
	s_nop 0
	global_load_lds_dwordx4 v[228:229], off
	s_add_u32 s24, s24, 0x40000
	s_addc_u32 s25, s25, 0
	s_mov_b32 m0, s31
	v_lshl_add_u64 v[230:231], s[24:25], 0, v[134:135]
	ds_read_b128 v[192:195], v153 offset:32768
	ds_read_b128 v[196:199], v153 offset:33792
	ds_read_b128 v[200:203], v153 offset:34816
	ds_read_b128 v[204:207], v153 offset:35840
	ds_read_b128 v[208:211], v153 offset:36864
	ds_read_b128 v[212:215], v153 offset:37888
	ds_read_b128 v[216:219], v153 offset:38912
	ds_read_b128 v[220:223], v153 offset:39936
	global_load_lds_dwordx4 v[230:231], off
	v_lshl_add_u64 v[230:231], s[24:25], 0, v[130:131]
	s_mov_b32 m0, s33
	s_nop 0
	global_load_lds_dwordx4 v[230:231], off
	s_waitcnt vmcnt(8)
	s_waitcnt lgkmcnt(0)
	s_barrier
	s_waitcnt lgkmcnt(0)
	v_mfma_f32_16x16x32_bf16 v[124:127], v[154:157], v[192:195], v[124:127]
	v_mfma_f32_16x16x32_bf16 v[116:119], v[162:165], v[192:195], v[116:119]
	v_mfma_f32_16x16x32_bf16 v[108:111], v[154:157], v[200:203], v[108:111]
	v_mfma_f32_16x16x32_bf16 v[100:103], v[162:165], v[200:203], v[100:103]
	v_mfma_f32_16x16x32_bf16 v[92:95], v[154:157], v[208:211], v[92:95]
	v_mfma_f32_16x16x32_bf16 v[84:87], v[162:165], v[208:211], v[84:87]
	v_mfma_f32_16x16x32_bf16 v[76:79], v[154:157], v[216:219], v[76:79]
	v_mfma_f32_16x16x32_bf16 v[68:71], v[162:165], v[216:219], v[68:71]
	v_mfma_f32_16x16x32_bf16 v[124:127], v[158:161], v[196:199], v[124:127]
	v_mfma_f32_16x16x32_bf16 v[116:119], v[166:169], v[196:199], v[116:119]
	v_mfma_f32_16x16x32_bf16 v[108:111], v[158:161], v[204:207], v[108:111]
	v_mfma_f32_16x16x32_bf16 v[100:103], v[166:169], v[204:207], v[100:103]
	v_mfma_f32_16x16x32_bf16 v[92:95], v[158:161], v[212:215], v[92:95]
	v_mfma_f32_16x16x32_bf16 v[84:87], v[166:169], v[212:215], v[84:87]
	v_mfma_f32_16x16x32_bf16 v[76:79], v[158:161], v[220:223], v[76:79]
	v_mfma_f32_16x16x32_bf16 v[68:71], v[166:169], v[220:223], v[68:71]
	v_mfma_f32_16x16x32_bf16 v[120:123], v[170:173], v[192:195], v[120:123]
	v_mfma_f32_16x16x32_bf16 v[112:115], v[184:187], v[192:195], v[112:115]
	v_mfma_f32_16x16x32_bf16 v[104:107], v[170:173], v[200:203], v[104:107]
	v_mfma_f32_16x16x32_bf16 v[96:99], v[184:187], v[200:203], v[96:99]
	v_mfma_f32_16x16x32_bf16 v[88:91], v[170:173], v[208:211], v[88:91]
	v_mfma_f32_16x16x32_bf16 v[80:83], v[184:187], v[208:211], v[80:83]
	v_mfma_f32_16x16x32_bf16 v[72:75], v[170:173], v[216:219], v[72:75]
	v_mfma_f32_16x16x32_bf16 v[64:67], v[184:187], v[216:219], v[64:67]
	v_mfma_f32_16x16x32_bf16 v[120:123], v[174:177], v[196:199], v[120:123]
	v_mfma_f32_16x16x32_bf16 v[112:115], v[188:191], v[196:199], v[112:115]
	v_mfma_f32_16x16x32_bf16 v[104:107], v[174:177], v[204:207], v[104:107]
	v_mfma_f32_16x16x32_bf16 v[96:99], v[188:191], v[204:207], v[96:99]
	v_mfma_f32_16x16x32_bf16 v[88:91], v[174:177], v[212:215], v[88:91]
	v_mfma_f32_16x16x32_bf16 v[80:83], v[188:191], v[212:215], v[80:83]
	s_setprio 3
	s_barrier
	v_mfma_f32_16x16x32_bf16 v[72:75], v[174:177], v[220:223], v[72:75]
	v_mfma_f32_16x16x32_bf16 v[64:67], v[188:191], v[220:223], v[64:67]
	s_setprio 0
	s_add_i32 s24, s47, s28
	v_lshl_add_u64 v[178:179], v[178:179], 0, s[6:7]
	s_mov_b32 m0, s24
	ds_read_b128 v[192:195], v153 offset:49152
	ds_read_b128 v[196:199], v153 offset:50176
	ds_read_b128 v[200:203], v153 offset:51200
	ds_read_b128 v[204:207], v153 offset:52224
	ds_read_b128 v[208:211], v153 offset:53248
	ds_read_b128 v[212:215], v153 offset:54272
	ds_read_b128 v[216:219], v153 offset:55296
	ds_read_b128 v[220:223], v153 offset:56320
	global_load_lds_dwordx4 v[178:179], off
	s_add_i32 m0, s24, 0x2000
	s_add_u32 s22, s22, 0x40080
	v_lshl_add_u64 v[178:179], v[224:225], 0, s[6:7]
	s_addc_u32 s23, s23, 0
	s_add_i32 s24, s48, s28
	global_load_lds_dwordx4 v[178:179], off
	v_lshl_add_u64 v[178:179], s[22:23], 0, v[132:133]
	s_mov_b32 m0, s24
	s_nop 0
	global_load_lds_dwordx4 v[178:179], off
	v_lshl_add_u64 v[178:179], s[22:23], 0, v[128:129]
	s_add_i32 m0, s24, 0x2000
	s_nop 0
	global_load_lds_dwordx4 v[178:179], off
	s_waitcnt vmcnt(6)
	s_waitcnt lgkmcnt(0)
	s_barrier
	s_waitcnt lgkmcnt(0)
	v_mfma_f32_16x16x32_bf16 v[60:63], v[154:157], v[192:195], v[60:63]
	v_mfma_f32_16x16x32_bf16 v[52:55], v[162:165], v[192:195], v[52:55]
	v_mfma_f32_16x16x32_bf16 v[44:47], v[154:157], v[200:203], v[44:47]
	v_mfma_f32_16x16x32_bf16 v[36:39], v[162:165], v[200:203], v[36:39]
	v_mfma_f32_16x16x32_bf16 v[28:31], v[154:157], v[208:211], v[28:31]
	v_mfma_f32_16x16x32_bf16 v[20:23], v[162:165], v[208:211], v[20:23]
	v_mfma_f32_16x16x32_bf16 v[12:15], v[154:157], v[216:219], v[12:15]
	v_mfma_f32_16x16x32_bf16 v[4:7], v[162:165], v[216:219], v[4:7]
	v_mfma_f32_16x16x32_bf16 v[60:63], v[158:161], v[196:199], v[60:63]
	v_mfma_f32_16x16x32_bf16 v[52:55], v[166:169], v[196:199], v[52:55]
	v_mfma_f32_16x16x32_bf16 v[44:47], v[158:161], v[204:207], v[44:47]
	v_mfma_f32_16x16x32_bf16 v[36:39], v[166:169], v[204:207], v[36:39]
	v_mfma_f32_16x16x32_bf16 v[28:31], v[158:161], v[212:215], v[28:31]
	v_mfma_f32_16x16x32_bf16 v[20:23], v[166:169], v[212:215], v[20:23]
	v_mfma_f32_16x16x32_bf16 v[12:15], v[158:161], v[220:223], v[12:15]
	v_mfma_f32_16x16x32_bf16 v[4:7], v[166:169], v[220:223], v[4:7]
	v_mfma_f32_16x16x32_bf16 v[56:59], v[170:173], v[192:195], v[56:59]
	v_mfma_f32_16x16x32_bf16 v[48:51], v[184:187], v[192:195], v[48:51]
	v_mfma_f32_16x16x32_bf16 v[40:43], v[170:173], v[200:203], v[40:43]
	v_mfma_f32_16x16x32_bf16 v[32:35], v[184:187], v[200:203], v[32:35]
	v_mfma_f32_16x16x32_bf16 v[24:27], v[170:173], v[208:211], v[24:27]
	v_mfma_f32_16x16x32_bf16 v[16:19], v[184:187], v[208:211], v[16:19]
	v_mfma_f32_16x16x32_bf16 v[8:11], v[170:173], v[216:219], v[8:11]
	v_mfma_f32_16x16x32_bf16 v[0:3], v[184:187], v[216:219], v[0:3]
	v_mfma_f32_16x16x32_bf16 v[56:59], v[174:177], v[196:199], v[56:59]
	v_mfma_f32_16x16x32_bf16 v[48:51], v[188:191], v[196:199], v[48:51]
	v_mfma_f32_16x16x32_bf16 v[40:43], v[174:177], v[204:207], v[40:43]
	v_mfma_f32_16x16x32_bf16 v[32:35], v[188:191], v[204:207], v[32:35]
	v_mfma_f32_16x16x32_bf16 v[24:27], v[174:177], v[212:215], v[24:27]
	v_mfma_f32_16x16x32_bf16 v[16:19], v[188:191], v[212:215], v[16:19]
	s_setprio 3
	s_barrier
	v_mfma_f32_16x16x32_bf16 v[8:11], v[174:177], v[220:223], v[8:11]
	v_mfma_f32_16x16x32_bf16 v[0:3], v[188:191], v[220:223], v[0:3]
	s_setprio 0
	v_lshl_add_u64 v[178:179], v[226:227], 0, s[6:7]
	s_mov_b32 m0, s34
	s_nop 0
	global_load_lds_dwordx4 v[178:179], off
	v_lshl_add_u64 v[178:179], v[228:229], 0, s[6:7]
	s_mov_b32 m0, s35
	s_nop 0
	global_load_lds_dwordx4 v[178:179], off
	s_add_i32 s46, s46, 2
	s_add_u32 s20, s20, 0x100
	s_addc_u32 s21, s21, 0
	s_add_u32 s44, s44, 0x100
	s_addc_u32 s45, s45, 0
	s_cmp_gt_u32 s46, 13
